# GLU / MLP-out A / O-proj epilogues: row sum-of-squares cross-lane steps via permlane16/32 swaps instead of ds_bpermute (on v41)
# baseline (speedup 1.0000x reference)
.LBB0_344:
	v_lshl_or_b32 v162, s8, 7, v172
	v_ashrrev_i32_e32 v163, 31, v162
	v_lshlrev_b64 v[82:83], 2, v[162:163]
	v_lshl_add_u64 v[86:87], s[16:17], 0, v[82:83]
	v_lshl_add_u64 v[102:103], s[20:21], 0, v[82:83]
	global_load_dwordx4 v[82:85], v[86:87], off offset:16
	global_load_dwordx4 v[94:97], v[86:87], off
	s_nop 0
	global_load_dwordx4 v[86:89], v[102:103], off offset:16
	s_nop 0
	global_load_dwordx4 v[102:105], v[102:103], off
	s_lshl_b32 s23, s30, 8
	v_add_u32_e32 v164, s23, v170
	v_ashrrev_i32_e32 v165, 31, v164
	v_lshlrev_b64 v[134:135], 11, v[164:165]
	v_lshl_add_u64 v[134:135], s[14:15], 0, v[134:135]
	v_lshlrev_b64 v[136:137], 1, v[162:163]
	v_lshl_add_u64 v[182:183], v[134:135], 0, v[136:137]
	global_load_dwordx4 v[178:181], v[182:183], off
	v_add_u32_e32 v166, s23, v173
	v_ashrrev_i32_e32 v167, 31, v166
	v_lshlrev_b64 v[134:135], 11, v[166:167]
	v_lshl_add_u64 v[134:135], s[14:15], 0, v[134:135]
	v_lshl_add_u64 v[168:169], v[134:135], 0, v[136:137]
	global_load_dwordx4 v[134:137], v[168:169], off
	s_waitcnt vmcnt(0)
	v_add_f32_e32 v138, v138, v82
	v_add_f32_e32 v146, v146, v94
	v_add_f32_e32 v130, v130, v86
	v_mul_f32_e32 v130, 0xbfb8aa3b, v130
	v_add_f32_e32 v131, v131, v87
	v_add_f32_e32 v142, v142, v102
	v_exp_f32_e32 v130, v130
	v_mul_f32_e32 v131, 0xbfb8aa3b, v131
	v_mul_f32_e32 v142, 0xbfb8aa3b, v142
	v_add_f32_e32 v143, v143, v103
	v_exp_f32_e32 v131, v131
	v_exp_f32_e32 v142, v142
	v_mul_f32_e32 v143, 0xbfb8aa3b, v143
	v_exp_f32_e32 v143, v143
	v_add_f32_e32 v130, 1.0, v130
	v_rcp_f32_e32 v130, v130
	v_add_f32_e32 v131, 1.0, v131
	v_add_f32_e32 v142, 1.0, v142
	v_rcp_f32_e32 v131, v131
	v_rcp_f32_e32 v142, v142
	v_add_f32_e32 v143, 1.0, v143
	v_lshlrev_b32_e32 v185, 16, v180
	v_rcp_f32_e32 v143, v143
	v_and_b32_e32 v180, 0xffff0000, v180
	v_fmac_f32_e32 v185, v138, v130
	v_add_f32_e32 v130, v139, v83
	v_lshlrev_b32_e32 v177, 16, v178
	v_fmac_f32_e32 v180, v130, v131
	v_add_f32_e32 v131, v132, v88
	v_and_b32_e32 v178, 0xffff0000, v178
	v_fmac_f32_e32 v177, v146, v142
	v_add_f32_e32 v142, v147, v95
	v_mul_f32_e32 v131, 0xbfb8aa3b, v131
	v_fmac_f32_e32 v178, v142, v143
	v_add_f32_e32 v143, v144, v104
	v_exp_f32_e32 v131, v131
	v_mul_f32_e32 v143, 0xbfb8aa3b, v143
	v_exp_f32_e32 v143, v143
	v_lshlrev_b32_e32 v186, 16, v181
	v_add_f32_e32 v131, 1.0, v131
	v_rcp_f32_e32 v131, v131
	v_add_f32_e32 v143, 1.0, v143
	v_rcp_f32_e32 v143, v143
	v_add_f32_e32 v130, v140, v84
	v_fmac_f32_e32 v186, v130, v131
	v_add_f32_e32 v131, v133, v89
	v_lshlrev_b32_e32 v184, 16, v179
	v_add_f32_e32 v142, v148, v96
	v_mul_f32_e32 v131, 0xbfb8aa3b, v131
	v_fmac_f32_e32 v184, v142, v143
	v_add_f32_e32 v143, v145, v105
	v_exp_f32_e32 v131, v131
	v_mul_f32_e32 v143, 0xbfb8aa3b, v143
	v_exp_f32_e32 v143, v143
	v_and_b32_e32 v181, 0xffff0000, v181
	v_add_f32_e32 v131, 1.0, v131
	v_rcp_f32_e32 v131, v131
	v_add_f32_e32 v143, 1.0, v143
	v_rcp_f32_e32 v143, v143
	v_add_f32_e32 v130, v141, v85
	v_fmac_f32_e32 v181, v130, v131
	v_and_b32_e32 v179, 0xffff0000, v179
	v_add_f32_e32 v142, v149, v97
	v_mul_f32_e32 v130, v180, v180
	v_mul_f32_e32 v131, v181, v181
	v_fmac_f32_e32 v179, v142, v143
	v_fmac_f32_e32 v130, v185, v185
	v_fmac_f32_e32 v131, v186, v186
	v_and_b32_e32 v132, 64, v1
	v_mul_f32_e32 v142, v178, v178
	v_mul_f32_e32 v143, v179, v179
	v_add_f32_e32 v130, v130, v131
	v_xor_b32_e32 v131, 16, v1
	v_add_u32_e32 v132, 64, v132
	v_fmac_f32_e32 v142, v177, v177
	v_fmac_f32_e32 v143, v184, v184
	v_cmp_lt_i32_e32 vcc, v131, v132
	v_add_f32_e32 v142, v142, v143
	v_add_f32_e32 v130, v142, v130
	v_cndmask_b32_e32 v131, v1, v131, vcc
	v_lshlrev_b32_e32 v142, 2, v131
	v_cvt_pk_bf16_f32 v138, v177, v178
	v_cvt_pk_bf16_f32 v139, v184, v179
	v_cvt_pk_bf16_f32 v140, v185, v180
	v_cvt_pk_bf16_f32 v141, v186, v181
	s_nop 0
	v_mov_b32_e32 v131, v130
	v_mov_b32_e32 v190, v130
	s_nop 1
	v_permlane16_swap_b32 v131, v190
	v_add_f32_e32 v130, v131, v190
	v_xor_b32_e32 v131, 32, v1
	v_cmp_lt_i32_e32 vcc, v131, v132
	global_store_dwordx4 v[182:183], v[138:141], off
	s_nop 0
	v_cndmask_b32_e32 v131, v1, v131, vcc
	v_lshlrev_b32_e32 v143, 2, v131
	v_mov_b32_e32 v131, v130
	v_mov_b32_e32 v190, v130
	s_nop 1
	v_permlane32_swap_b32 v190, v131
	s_and_saveexec_b64 s[30:31], s[0:1]
	s_cbranch_execz .LBB0_346
	s_nop 0
	v_add_f32_e32 v132, v130, v131
	s_lshl_b32 s34, s8, 2
	v_lshlrev_b64 v[130:131], 7, v[164:165]
	s_ashr_i32 s35, s34, 31
	v_lshl_add_u64 v[130:131], s[12:13], 0, v[130:131]
	v_lshl_add_u64 v[130:131], s[34:35], 2, v[130:131]
	s_lshl_b32 s40, s72, 2
	v_lshl_add_u64 v[130:131], v[130:131], 0, s[40:41]
	global_store_dword v[130:131], v132, off
.LBB0_346:
	s_or_b64 exec, exec, s[30:31]
	v_add_u32_e32 v138, s23, v174
	v_ashrrev_i32_e32 v139, 31, v138
	s_waitcnt lgkmcnt(0)
	v_lshlrev_b64 v[130:131], 11, v[138:139]
	v_lshl_add_u64 v[130:131], s[14:15], 0, v[130:131]
	v_lshl_add_u64 v[140:141], v[162:163], 1, v[130:131]
	global_load_dwordx4 v[130:133], v[140:141], off
	v_add_f32_e32 v122, v122, v102
	v_add_f32_e32 v114, v114, v86
	v_mul_f32_e32 v122, 0xbfb8aa3b, v122
	v_add_f32_e32 v123, v123, v103
	v_mul_f32_e32 v114, 0xbfb8aa3b, v114
	v_add_f32_e32 v115, v115, v87
	v_exp_f32_e32 v122, v122
	v_mul_f32_e32 v123, 0xbfb8aa3b, v123
	v_exp_f32_e32 v114, v114
	v_mul_f32_e32 v115, 0xbfb8aa3b, v115
	v_exp_f32_e32 v123, v123
	v_exp_f32_e32 v115, v115
	v_add_f32_e32 v122, 1.0, v122
	v_add_f32_e32 v124, v124, v104
	v_add_f32_e32 v114, 1.0, v114
	v_add_f32_e32 v116, v116, v88
	v_rcp_f32_e32 v122, v122
	v_add_f32_e32 v123, 1.0, v123
	v_mul_f32_e32 v124, 0xbfb8aa3b, v124
	v_add_f32_e32 v125, v125, v105
	v_rcp_f32_e32 v114, v114
	v_add_f32_e32 v115, 1.0, v115
	v_mul_f32_e32 v116, 0xbfb8aa3b, v116
	v_add_f32_e32 v117, v117, v89
	v_rcp_f32_e32 v123, v123
	v_exp_f32_e32 v124, v124
	v_mul_f32_e32 v125, 0xbfb8aa3b, v125
	v_rcp_f32_e32 v115, v115
	v_exp_f32_e32 v116, v116
	v_mul_f32_e32 v117, 0xbfb8aa3b, v117
	v_exp_f32_e32 v125, v125
	v_exp_f32_e32 v117, v117
	v_lshlrev_b32_e32 v144, 16, v134
	v_lshlrev_b32_e32 v146, 16, v136
	v_add_f32_e32 v126, v126, v94
	v_add_f32_e32 v118, v118, v82
	v_and_b32_e32 v134, 0xffff0000, v134
	v_and_b32_e32 v136, 0xffff0000, v136
	v_fmac_f32_e32 v144, v126, v122
	v_add_f32_e32 v122, v127, v95
	v_fmac_f32_e32 v146, v118, v114
	v_add_f32_e32 v114, v119, v83
	v_fmac_f32_e32 v134, v122, v123
	v_add_f32_e32 v122, 1.0, v124
	v_fmac_f32_e32 v136, v114, v115
	v_add_f32_e32 v114, 1.0, v116
	v_rcp_f32_e32 v122, v122
	v_add_f32_e32 v123, 1.0, v125
	v_rcp_f32_e32 v114, v114
	v_add_f32_e32 v115, 1.0, v117
	v_rcp_f32_e32 v123, v123
	v_rcp_f32_e32 v115, v115
	v_lshlrev_b32_e32 v145, 16, v135
	v_lshlrev_b32_e32 v147, 16, v137
	v_add_f32_e32 v124, v128, v96
	v_add_f32_e32 v116, v120, v84
	v_and_b32_e32 v135, 0xffff0000, v135
	v_and_b32_e32 v137, 0xffff0000, v137
	v_fmac_f32_e32 v145, v124, v122
	v_add_f32_e32 v122, v129, v97
	v_fmac_f32_e32 v147, v116, v114
	v_add_f32_e32 v114, v121, v85
	v_fmac_f32_e32 v135, v122, v123
	v_fmac_f32_e32 v137, v114, v115
	v_mul_f32_e32 v122, v134, v134
	v_mul_f32_e32 v123, v135, v135
	v_mul_f32_e32 v114, v136, v136
	v_mul_f32_e32 v115, v137, v137
	v_fmac_f32_e32 v122, v144, v144
	v_fmac_f32_e32 v123, v145, v145
	v_fmac_f32_e32 v114, v146, v146
	v_fmac_f32_e32 v115, v147, v147
	v_add_f32_e32 v122, v122, v123
	v_add_f32_e32 v114, v114, v115
	v_add_f32_e32 v114, v122, v114
	v_cvt_pk_bf16_f32 v116, v144, v134
	v_cvt_pk_bf16_f32 v117, v145, v135
	v_cvt_pk_bf16_f32 v118, v146, v136
	s_nop 0
	v_mov_b32_e32 v115, v114
	v_mov_b32_e32 v190, v114
	s_nop 1
	v_permlane16_swap_b32 v115, v190
	v_add_f32_e32 v114, v115, v190
	v_mov_b32_e32 v115, v114
	v_mov_b32_e32 v190, v114
	s_nop 1
	v_permlane32_swap_b32 v190, v115
	v_cvt_pk_bf16_f32 v119, v147, v137
	global_store_dwordx4 v[168:169], v[116:119], off
	s_and_saveexec_b64 s[30:31], s[0:1]
	s_cbranch_execz .LBB0_348
	s_nop 0
	v_add_f32_e32 v116, v114, v115
	s_lshl_b32 s34, s8, 2
	v_lshlrev_b64 v[114:115], 7, v[166:167]
	s_ashr_i32 s35, s34, 31
	v_lshl_add_u64 v[114:115], s[12:13], 0, v[114:115]
	v_lshl_add_u64 v[114:115], s[34:35], 2, v[114:115]
	s_lshl_b32 s40, s72, 2
	v_lshl_add_u64 v[114:115], v[114:115], 0, s[40:41]
	global_store_dword v[114:115], v116, off
.LBB0_348:
	s_or_b64 exec, exec, s[30:31]
	v_add_u32_e32 v118, s23, v175
	v_ashrrev_i32_e32 v119, 31, v118
	s_waitcnt lgkmcnt(0)
	v_lshlrev_b64 v[114:115], 11, v[118:119]
	v_lshl_add_u64 v[114:115], s[14:15], 0, v[114:115]
	v_lshl_add_u64 v[120:121], v[162:163], 1, v[114:115]
	global_load_dwordx4 v[114:117], v[120:121], off
	v_add_f32_e32 v106, v106, v102
	v_add_f32_e32 v90, v90, v86
	v_mul_f32_e32 v106, 0xbfb8aa3b, v106
	v_add_f32_e32 v107, v107, v103
	v_mul_f32_e32 v90, 0xbfb8aa3b, v90
	v_add_f32_e32 v91, v91, v87
	v_exp_f32_e32 v106, v106
	v_mul_f32_e32 v107, 0xbfb8aa3b, v107
	v_exp_f32_e32 v90, v90
	v_mul_f32_e32 v91, 0xbfb8aa3b, v91
	v_exp_f32_e32 v107, v107
	v_exp_f32_e32 v91, v91
	v_add_f32_e32 v106, 1.0, v106
	v_add_f32_e32 v108, v108, v104
	v_add_f32_e32 v90, 1.0, v90
	v_add_f32_e32 v92, v92, v88
	v_rcp_f32_e32 v106, v106
	v_add_f32_e32 v107, 1.0, v107
	v_mul_f32_e32 v108, 0xbfb8aa3b, v108
	v_add_f32_e32 v109, v109, v105
	v_rcp_f32_e32 v90, v90
	v_add_f32_e32 v91, 1.0, v91
	v_mul_f32_e32 v92, 0xbfb8aa3b, v92
	v_add_f32_e32 v93, v93, v89
	v_rcp_f32_e32 v107, v107
	v_exp_f32_e32 v108, v108
	v_mul_f32_e32 v109, 0xbfb8aa3b, v109
	v_rcp_f32_e32 v91, v91
	v_exp_f32_e32 v92, v92
	v_mul_f32_e32 v93, 0xbfb8aa3b, v93
	v_exp_f32_e32 v109, v109
	v_exp_f32_e32 v93, v93
	s_waitcnt vmcnt(2)
	v_lshlrev_b32_e32 v122, 16, v130
	v_lshlrev_b32_e32 v126, 16, v132
	v_add_f32_e32 v110, v110, v94
	v_add_f32_e32 v98, v98, v82
	v_and_b32_e32 v123, 0xffff0000, v130
	v_and_b32_e32 v127, 0xffff0000, v132
	v_fmac_f32_e32 v122, v110, v106
	v_add_f32_e32 v106, v111, v95
	v_fmac_f32_e32 v126, v98, v90
	v_add_f32_e32 v90, v99, v83
	v_fmac_f32_e32 v123, v106, v107
	v_add_f32_e32 v106, 1.0, v108
	v_fmac_f32_e32 v127, v90, v91
	v_add_f32_e32 v90, 1.0, v92
	v_rcp_f32_e32 v106, v106
	v_add_f32_e32 v107, 1.0, v109
	v_rcp_f32_e32 v90, v90
	v_add_f32_e32 v91, 1.0, v93
	v_rcp_f32_e32 v107, v107
	v_rcp_f32_e32 v91, v91
	v_lshlrev_b32_e32 v124, 16, v131
	v_lshlrev_b32_e32 v128, 16, v133
	v_add_f32_e32 v108, v112, v96
	v_add_f32_e32 v92, v100, v84
	v_and_b32_e32 v125, 0xffff0000, v131
	v_and_b32_e32 v129, 0xffff0000, v133
	v_fmac_f32_e32 v124, v108, v106
	v_add_f32_e32 v106, v113, v97
	v_fmac_f32_e32 v128, v92, v90
	v_add_f32_e32 v90, v101, v85
	v_fmac_f32_e32 v125, v106, v107
	v_fmac_f32_e32 v129, v90, v91
	v_mul_f32_e32 v106, v123, v123
	v_mul_f32_e32 v107, v125, v125
	v_mul_f32_e32 v90, v127, v127
	v_mul_f32_e32 v91, v129, v129
	v_fmac_f32_e32 v106, v122, v122
	v_fmac_f32_e32 v107, v124, v124
	v_fmac_f32_e32 v90, v126, v126
	v_fmac_f32_e32 v91, v128, v128
	v_add_f32_e32 v106, v106, v107
	v_add_f32_e32 v90, v90, v91
	v_add_f32_e32 v90, v106, v90
	v_cvt_pk_bf16_f32 v98, v122, v123
	v_cvt_pk_bf16_f32 v99, v124, v125
	v_cvt_pk_bf16_f32 v100, v126, v127
	s_nop 0
	v_mov_b32_e32 v91, v90
	v_mov_b32_e32 v190, v90
	s_nop 1
	v_permlane16_swap_b32 v91, v190
	v_add_f32_e32 v90, v91, v190
	v_mov_b32_e32 v91, v90
	v_mov_b32_e32 v190, v90
	s_nop 1
	v_permlane32_swap_b32 v190, v91
	v_cvt_pk_bf16_f32 v101, v128, v129
	global_store_dwordx4 v[140:141], v[98:101], off
	s_and_saveexec_b64 s[30:31], s[0:1]
	s_cbranch_execz .LBB0_350
	s_nop 0
	v_add_f32_e32 v92, v90, v91
	s_lshl_b32 s34, s8, 2
	v_lshlrev_b64 v[90:91], 7, v[138:139]
	s_ashr_i32 s35, s34, 31
	v_lshl_add_u64 v[90:91], s[12:13], 0, v[90:91]
	v_lshl_add_u64 v[90:91], s[34:35], 2, v[90:91]
	s_lshl_b32 s40, s72, 2
	v_lshl_add_u64 v[90:91], v[90:91], 0, s[40:41]
	global_store_dword v[90:91], v92, off
.LBB0_350:
	s_or_b64 exec, exec, s[30:31]
	v_add_u32_e32 v98, 0x80, v164
	v_ashrrev_i32_e32 v99, 31, v98
	s_waitcnt lgkmcnt(0)
	v_lshlrev_b64 v[90:91], 11, v[98:99]
	v_lshl_add_u64 v[90:91], s[14:15], 0, v[90:91]
	v_lshl_add_u64 v[100:101], v[162:163], 1, v[90:91]
	global_load_dwordx4 v[90:93], v[100:101], off
	v_add_f32_e32 v74, v74, v102
	v_add_f32_e32 v66, v66, v86
	v_mul_f32_e32 v74, 0xbfb8aa3b, v74
	v_add_f32_e32 v75, v75, v103
	v_mul_f32_e32 v66, 0xbfb8aa3b, v66
	v_add_f32_e32 v67, v67, v87
	v_exp_f32_e32 v74, v74
	v_mul_f32_e32 v75, 0xbfb8aa3b, v75
	v_exp_f32_e32 v66, v66
	v_mul_f32_e32 v67, 0xbfb8aa3b, v67
	v_exp_f32_e32 v75, v75
	v_exp_f32_e32 v67, v67
	v_add_f32_e32 v74, 1.0, v74
	v_add_f32_e32 v76, v76, v104
	v_add_f32_e32 v66, 1.0, v66
	v_add_f32_e32 v68, v68, v88
	v_rcp_f32_e32 v74, v74
	v_add_f32_e32 v75, 1.0, v75
	v_mul_f32_e32 v76, 0xbfb8aa3b, v76
	v_add_f32_e32 v77, v77, v105
	v_rcp_f32_e32 v66, v66
	v_add_f32_e32 v67, 1.0, v67
	v_mul_f32_e32 v68, 0xbfb8aa3b, v68
	v_add_f32_e32 v69, v69, v89
	v_rcp_f32_e32 v75, v75
	v_exp_f32_e32 v76, v76
	v_mul_f32_e32 v77, 0xbfb8aa3b, v77
	v_rcp_f32_e32 v67, v67
	v_exp_f32_e32 v68, v68
	v_mul_f32_e32 v69, 0xbfb8aa3b, v69
	v_exp_f32_e32 v77, v77
	v_exp_f32_e32 v69, v69
	s_waitcnt vmcnt(2)
	v_lshlrev_b32_e32 v106, 16, v114
	v_lshlrev_b32_e32 v110, 16, v116
	v_add_f32_e32 v78, v78, v94
	v_add_f32_e32 v70, v70, v82
	v_and_b32_e32 v107, 0xffff0000, v114
	v_and_b32_e32 v111, 0xffff0000, v116
	v_fmac_f32_e32 v106, v78, v74
	v_add_f32_e32 v74, v79, v95
	v_fmac_f32_e32 v110, v70, v66
	v_add_f32_e32 v66, v71, v83
	v_fmac_f32_e32 v107, v74, v75
	v_add_f32_e32 v74, 1.0, v76
	v_fmac_f32_e32 v111, v66, v67
	v_add_f32_e32 v66, 1.0, v68
	v_rcp_f32_e32 v74, v74
	v_add_f32_e32 v75, 1.0, v77
	v_rcp_f32_e32 v66, v66
	v_add_f32_e32 v67, 1.0, v69
	v_rcp_f32_e32 v75, v75
	v_rcp_f32_e32 v67, v67
	v_lshlrev_b32_e32 v108, 16, v115
	v_lshlrev_b32_e32 v112, 16, v117
	v_add_f32_e32 v76, v80, v96
	v_add_f32_e32 v68, v72, v84
	v_and_b32_e32 v109, 0xffff0000, v115
	v_and_b32_e32 v113, 0xffff0000, v117
	v_fmac_f32_e32 v108, v76, v74
	v_add_f32_e32 v74, v81, v97
	v_fmac_f32_e32 v112, v68, v66
	v_add_f32_e32 v66, v73, v85
	v_fmac_f32_e32 v109, v74, v75
	v_fmac_f32_e32 v113, v66, v67
	v_mul_f32_e32 v74, v107, v107
	v_mul_f32_e32 v75, v109, v109
	v_mul_f32_e32 v66, v111, v111
	v_mul_f32_e32 v67, v113, v113
	v_fmac_f32_e32 v74, v106, v106
	v_fmac_f32_e32 v75, v108, v108
	v_fmac_f32_e32 v66, v110, v110
	v_fmac_f32_e32 v67, v112, v112
	v_add_f32_e32 v74, v74, v75
	v_add_f32_e32 v66, v66, v67
	v_add_f32_e32 v66, v74, v66
	v_cvt_pk_bf16_f32 v68, v106, v107
	v_cvt_pk_bf16_f32 v69, v108, v109
	v_cvt_pk_bf16_f32 v70, v110, v111
	s_nop 0
	v_mov_b32_e32 v67, v66
	v_mov_b32_e32 v190, v66
	s_nop 1
	v_permlane16_swap_b32 v67, v190
	v_add_f32_e32 v66, v67, v190
	v_mov_b32_e32 v67, v66
	v_mov_b32_e32 v190, v66
	s_nop 1
	v_permlane32_swap_b32 v190, v67
	v_cvt_pk_bf16_f32 v71, v112, v113
	global_store_dwordx4 v[120:121], v[68:71], off
	s_and_saveexec_b64 s[30:31], s[0:1]
	s_cbranch_execz .LBB0_352
	s_nop 0
	v_add_f32_e32 v68, v66, v67
	s_lshl_b32 s34, s8, 2
	v_lshlrev_b64 v[66:67], 7, v[118:119]
	s_ashr_i32 s35, s34, 31
	v_lshl_add_u64 v[66:67], s[12:13], 0, v[66:67]
	v_lshl_add_u64 v[66:67], s[34:35], 2, v[66:67]
	s_lshl_b32 s40, s72, 2
	v_lshl_add_u64 v[66:67], v[66:67], 0, s[40:41]
	global_store_dword v[66:67], v68, off
.LBB0_352:
	s_or_b64 exec, exec, s[30:31]
	v_add_u32_e32 v70, 0x90, v164
	v_ashrrev_i32_e32 v71, 31, v70
	s_waitcnt lgkmcnt(0)
	v_lshlrev_b64 v[66:67], 11, v[70:71]
	v_lshl_add_u64 v[66:67], s[14:15], 0, v[66:67]
	v_lshl_add_u64 v[72:73], v[162:163], 1, v[66:67]
	global_load_dwordx4 v[66:69], v[72:73], off
	v_add_f32_e32 v58, v58, v102
	v_add_f32_e32 v50, v50, v86
	v_mul_f32_e32 v58, 0xbfb8aa3b, v58
	v_add_f32_e32 v59, v59, v103
	v_mul_f32_e32 v50, 0xbfb8aa3b, v50
	v_add_f32_e32 v51, v51, v87
	v_exp_f32_e32 v58, v58
	v_mul_f32_e32 v59, 0xbfb8aa3b, v59
	v_exp_f32_e32 v50, v50
	v_mul_f32_e32 v51, 0xbfb8aa3b, v51
	v_exp_f32_e32 v59, v59
	v_exp_f32_e32 v51, v51
	v_add_f32_e32 v58, 1.0, v58
	v_add_f32_e32 v60, v60, v104
	v_add_f32_e32 v50, 1.0, v50
	v_add_f32_e32 v52, v52, v88
	v_rcp_f32_e32 v58, v58
	v_add_f32_e32 v59, 1.0, v59
	v_mul_f32_e32 v60, 0xbfb8aa3b, v60
	v_add_f32_e32 v61, v61, v105
	v_rcp_f32_e32 v50, v50
	v_add_f32_e32 v51, 1.0, v51
	v_mul_f32_e32 v52, 0xbfb8aa3b, v52
	v_add_f32_e32 v53, v53, v89
	v_rcp_f32_e32 v59, v59
	v_exp_f32_e32 v60, v60
	v_mul_f32_e32 v61, 0xbfb8aa3b, v61
	v_rcp_f32_e32 v51, v51
	v_exp_f32_e32 v52, v52
	v_mul_f32_e32 v53, 0xbfb8aa3b, v53
	v_exp_f32_e32 v61, v61
	v_exp_f32_e32 v53, v53
	s_waitcnt vmcnt(2)
	v_lshlrev_b32_e32 v74, 16, v90
	v_lshlrev_b32_e32 v78, 16, v92
	v_add_f32_e32 v62, v62, v94
	v_add_f32_e32 v54, v54, v82
	v_and_b32_e32 v75, 0xffff0000, v90
	v_and_b32_e32 v79, 0xffff0000, v92
	v_fmac_f32_e32 v74, v62, v58
	v_add_f32_e32 v58, v63, v95
	v_fmac_f32_e32 v78, v54, v50
	v_add_f32_e32 v50, v55, v83
	v_fmac_f32_e32 v75, v58, v59
	v_add_f32_e32 v58, 1.0, v60
	v_fmac_f32_e32 v79, v50, v51
	v_add_f32_e32 v50, 1.0, v52
	v_rcp_f32_e32 v58, v58
	v_add_f32_e32 v59, 1.0, v61
	v_rcp_f32_e32 v50, v50
	v_add_f32_e32 v51, 1.0, v53
	v_rcp_f32_e32 v59, v59
	v_rcp_f32_e32 v51, v51
	v_lshlrev_b32_e32 v76, 16, v91
	v_lshlrev_b32_e32 v80, 16, v93
	v_add_f32_e32 v60, v64, v96
	v_add_f32_e32 v52, v56, v84
	v_and_b32_e32 v77, 0xffff0000, v91
	v_and_b32_e32 v81, 0xffff0000, v93
	v_fmac_f32_e32 v76, v60, v58
	v_add_f32_e32 v58, v65, v97
	v_fmac_f32_e32 v80, v52, v50
	v_add_f32_e32 v50, v57, v85
	v_fmac_f32_e32 v77, v58, v59
	v_fmac_f32_e32 v81, v50, v51
	v_mul_f32_e32 v58, v75, v75
	v_mul_f32_e32 v59, v77, v77
	v_mul_f32_e32 v50, v79, v79
	v_mul_f32_e32 v51, v81, v81
	v_fmac_f32_e32 v58, v74, v74
	v_fmac_f32_e32 v59, v76, v76
	v_fmac_f32_e32 v50, v78, v78
	v_fmac_f32_e32 v51, v80, v80
	v_add_f32_e32 v58, v58, v59
	v_add_f32_e32 v50, v50, v51
	v_add_f32_e32 v50, v58, v50
	v_cvt_pk_bf16_f32 v52, v74, v75
	v_cvt_pk_bf16_f32 v53, v76, v77
	v_cvt_pk_bf16_f32 v54, v78, v79
	s_nop 0
	v_mov_b32_e32 v51, v50
	v_mov_b32_e32 v190, v50
	s_nop 1
	v_permlane16_swap_b32 v51, v190
	v_add_f32_e32 v50, v51, v190
	v_mov_b32_e32 v51, v50
	v_mov_b32_e32 v190, v50
	s_nop 1
	v_permlane32_swap_b32 v190, v51
	v_cvt_pk_bf16_f32 v55, v80, v81
	global_store_dwordx4 v[100:101], v[52:55], off
	s_and_saveexec_b64 s[30:31], s[0:1]
	s_cbranch_execz .LBB0_354
	s_nop 0
	v_add_f32_e32 v52, v50, v51
	s_lshl_b32 s34, s8, 2
	v_lshlrev_b64 v[50:51], 7, v[98:99]
	s_ashr_i32 s35, s34, 31
	v_lshl_add_u64 v[50:51], s[12:13], 0, v[50:51]
	v_lshl_add_u64 v[50:51], s[34:35], 2, v[50:51]
	s_lshl_b32 s40, s72, 2
	v_lshl_add_u64 v[50:51], v[50:51], 0, s[40:41]
	global_store_dword v[50:51], v52, off
.LBB0_354:
	s_or_b64 exec, exec, s[30:31]
	v_add_u32_e32 v54, 0xa0, v164
	v_ashrrev_i32_e32 v55, 31, v54
	s_waitcnt lgkmcnt(0)
	v_lshlrev_b64 v[50:51], 11, v[54:55]
	v_lshl_add_u64 v[50:51], s[14:15], 0, v[50:51]
	v_lshl_add_u64 v[56:57], v[162:163], 1, v[50:51]
	global_load_dwordx4 v[50:53], v[56:57], off
	v_add_f32_e32 v42, v42, v102
	v_add_f32_e32 v34, v34, v86
	v_mul_f32_e32 v42, 0xbfb8aa3b, v42
	v_add_f32_e32 v43, v43, v103
	v_mul_f32_e32 v34, 0xbfb8aa3b, v34
	v_add_f32_e32 v35, v35, v87
	v_exp_f32_e32 v42, v42
	v_mul_f32_e32 v43, 0xbfb8aa3b, v43
	v_exp_f32_e32 v34, v34
	v_mul_f32_e32 v35, 0xbfb8aa3b, v35
	v_exp_f32_e32 v43, v43
	v_exp_f32_e32 v35, v35
	v_add_f32_e32 v42, 1.0, v42
	v_add_f32_e32 v44, v44, v104
	v_add_f32_e32 v34, 1.0, v34
	v_add_f32_e32 v36, v36, v88
	v_rcp_f32_e32 v42, v42
	v_add_f32_e32 v43, 1.0, v43
	v_mul_f32_e32 v44, 0xbfb8aa3b, v44
	v_add_f32_e32 v45, v45, v105
	v_rcp_f32_e32 v34, v34
	v_add_f32_e32 v35, 1.0, v35
	v_mul_f32_e32 v36, 0xbfb8aa3b, v36
	v_add_f32_e32 v37, v37, v89
	v_rcp_f32_e32 v43, v43
	v_exp_f32_e32 v44, v44
	v_mul_f32_e32 v45, 0xbfb8aa3b, v45
	v_rcp_f32_e32 v35, v35
	v_exp_f32_e32 v36, v36
	v_mul_f32_e32 v37, 0xbfb8aa3b, v37
	v_exp_f32_e32 v45, v45
	v_exp_f32_e32 v37, v37
	s_waitcnt vmcnt(2)
	v_lshlrev_b32_e32 v58, 16, v66
	v_lshlrev_b32_e32 v62, 16, v68
	v_add_f32_e32 v46, v46, v94
	v_add_f32_e32 v38, v38, v82
	v_and_b32_e32 v59, 0xffff0000, v66
	v_and_b32_e32 v63, 0xffff0000, v68
	v_fmac_f32_e32 v58, v46, v42
	v_add_f32_e32 v42, v47, v95
	v_fmac_f32_e32 v62, v38, v34
	v_add_f32_e32 v34, v39, v83
	v_fmac_f32_e32 v59, v42, v43
	v_add_f32_e32 v42, 1.0, v44
	v_fmac_f32_e32 v63, v34, v35
	v_add_f32_e32 v34, 1.0, v36
	v_rcp_f32_e32 v42, v42
	v_add_f32_e32 v43, 1.0, v45
	v_rcp_f32_e32 v34, v34
	v_add_f32_e32 v35, 1.0, v37
	v_rcp_f32_e32 v43, v43
	v_rcp_f32_e32 v35, v35
	v_lshlrev_b32_e32 v60, 16, v67
	v_lshlrev_b32_e32 v64, 16, v69
	v_add_f32_e32 v44, v48, v96
	v_add_f32_e32 v36, v40, v84
	v_and_b32_e32 v61, 0xffff0000, v67
	v_and_b32_e32 v65, 0xffff0000, v69
	v_fmac_f32_e32 v60, v44, v42
	v_add_f32_e32 v42, v49, v97
	v_fmac_f32_e32 v64, v36, v34
	v_add_f32_e32 v34, v41, v85
	v_fmac_f32_e32 v61, v42, v43
	v_fmac_f32_e32 v65, v34, v35
	v_mul_f32_e32 v42, v59, v59
	v_mul_f32_e32 v43, v61, v61
	v_mul_f32_e32 v34, v63, v63
	v_mul_f32_e32 v35, v65, v65
	v_fmac_f32_e32 v42, v58, v58
	v_fmac_f32_e32 v43, v60, v60
	v_fmac_f32_e32 v34, v62, v62
	v_fmac_f32_e32 v35, v64, v64
	v_add_f32_e32 v42, v42, v43
	v_add_f32_e32 v34, v34, v35
	v_add_f32_e32 v34, v42, v34
	v_cvt_pk_bf16_f32 v36, v58, v59
	v_cvt_pk_bf16_f32 v37, v60, v61
	v_cvt_pk_bf16_f32 v38, v62, v63
	s_nop 0
	v_mov_b32_e32 v35, v34
	v_mov_b32_e32 v190, v34
	s_nop 1
	v_permlane16_swap_b32 v35, v190
	v_add_f32_e32 v34, v35, v190
	v_mov_b32_e32 v35, v34
	v_mov_b32_e32 v190, v34
	s_nop 1
	v_permlane32_swap_b32 v190, v35
	v_cvt_pk_bf16_f32 v39, v64, v65
	global_store_dwordx4 v[72:73], v[36:39], off
	s_and_saveexec_b64 s[30:31], s[0:1]
	s_cbranch_execz .LBB0_356
	s_nop 0
	v_add_f32_e32 v36, v34, v35
	s_lshl_b32 s34, s8, 2
	v_lshlrev_b64 v[34:35], 7, v[70:71]
	s_ashr_i32 s35, s34, 31
	v_lshl_add_u64 v[34:35], s[12:13], 0, v[34:35]
	v_lshl_add_u64 v[34:35], s[34:35], 2, v[34:35]
	s_lshl_b32 s40, s72, 2
	v_lshl_add_u64 v[34:35], v[34:35], 0, s[40:41]
	global_store_dword v[34:35], v36, off
.LBB0_356:
	s_or_b64 exec, exec, s[30:31]
	v_add_u32_e32 v38, 0xb0, v164
	v_ashrrev_i32_e32 v39, 31, v38
	s_waitcnt lgkmcnt(0)
	v_lshlrev_b64 v[34:35], 11, v[38:39]
	v_lshl_add_u64 v[34:35], s[14:15], 0, v[34:35]
	v_lshl_add_u64 v[40:41], v[162:163], 1, v[34:35]
	global_load_dwordx4 v[34:37], v[40:41], off
	v_add_f32_e32 v26, v26, v102
	v_add_f32_e32 v18, v18, v86
	v_mul_f32_e32 v26, 0xbfb8aa3b, v26
	v_add_f32_e32 v27, v27, v103
	v_mul_f32_e32 v18, 0xbfb8aa3b, v18
	v_add_f32_e32 v19, v19, v87
	v_exp_f32_e32 v26, v26
	v_mul_f32_e32 v27, 0xbfb8aa3b, v27
	v_exp_f32_e32 v18, v18
	v_mul_f32_e32 v19, 0xbfb8aa3b, v19
	v_exp_f32_e32 v27, v27
	v_exp_f32_e32 v19, v19
	v_add_f32_e32 v26, 1.0, v26
	v_add_f32_e32 v28, v28, v104
	v_add_f32_e32 v18, 1.0, v18
	v_add_f32_e32 v20, v20, v88
	v_rcp_f32_e32 v26, v26
	v_add_f32_e32 v27, 1.0, v27
	v_mul_f32_e32 v28, 0xbfb8aa3b, v28
	v_add_f32_e32 v29, v29, v105
	v_rcp_f32_e32 v18, v18
	v_add_f32_e32 v19, 1.0, v19
	v_mul_f32_e32 v20, 0xbfb8aa3b, v20
	v_add_f32_e32 v21, v21, v89
	v_rcp_f32_e32 v27, v27
	v_exp_f32_e32 v28, v28
	v_mul_f32_e32 v29, 0xbfb8aa3b, v29
	v_rcp_f32_e32 v19, v19
	v_exp_f32_e32 v20, v20
	v_mul_f32_e32 v21, 0xbfb8aa3b, v21
	v_exp_f32_e32 v29, v29
	v_exp_f32_e32 v21, v21
	s_waitcnt vmcnt(2)
	v_lshlrev_b32_e32 v42, 16, v50
	v_lshlrev_b32_e32 v46, 16, v52
	v_add_f32_e32 v30, v30, v94
	v_add_f32_e32 v22, v22, v82
	v_and_b32_e32 v43, 0xffff0000, v50
	v_and_b32_e32 v47, 0xffff0000, v52
	v_fmac_f32_e32 v42, v30, v26
	v_add_f32_e32 v26, v31, v95
	v_fmac_f32_e32 v46, v22, v18
	v_add_f32_e32 v18, v23, v83
	v_fmac_f32_e32 v43, v26, v27
	v_add_f32_e32 v26, 1.0, v28
	v_fmac_f32_e32 v47, v18, v19
	v_add_f32_e32 v18, 1.0, v20
	v_rcp_f32_e32 v26, v26
	v_add_f32_e32 v27, 1.0, v29
	v_rcp_f32_e32 v18, v18
	v_add_f32_e32 v19, 1.0, v21
	v_rcp_f32_e32 v27, v27
	v_rcp_f32_e32 v19, v19
	v_lshlrev_b32_e32 v44, 16, v51
	v_lshlrev_b32_e32 v48, 16, v53
	v_add_f32_e32 v28, v32, v96
	v_add_f32_e32 v20, v24, v84
	v_and_b32_e32 v45, 0xffff0000, v51
	v_and_b32_e32 v49, 0xffff0000, v53
	v_fmac_f32_e32 v44, v28, v26
	v_add_f32_e32 v26, v33, v97
	v_fmac_f32_e32 v48, v20, v18
	v_add_f32_e32 v18, v25, v85
	v_fmac_f32_e32 v45, v26, v27
	v_fmac_f32_e32 v49, v18, v19
	v_mul_f32_e32 v26, v43, v43
	v_mul_f32_e32 v27, v45, v45
	v_mul_f32_e32 v18, v47, v47
	v_mul_f32_e32 v19, v49, v49
	v_fmac_f32_e32 v26, v42, v42
	v_fmac_f32_e32 v27, v44, v44
	v_fmac_f32_e32 v18, v46, v46
	v_fmac_f32_e32 v19, v48, v48
	v_add_f32_e32 v26, v26, v27
	v_add_f32_e32 v18, v18, v19
	v_add_f32_e32 v18, v26, v18
	v_cvt_pk_bf16_f32 v20, v42, v43
	v_cvt_pk_bf16_f32 v21, v44, v45
	v_cvt_pk_bf16_f32 v22, v46, v47
	s_nop 0
	v_mov_b32_e32 v19, v18
	v_mov_b32_e32 v190, v18
	s_nop 1
	v_permlane16_swap_b32 v19, v190
	v_add_f32_e32 v18, v19, v190
	v_mov_b32_e32 v19, v18
	v_mov_b32_e32 v190, v18
	s_nop 1
	v_permlane32_swap_b32 v190, v19
	v_cvt_pk_bf16_f32 v23, v48, v49
	global_store_dwordx4 v[56:57], v[20:23], off
	s_and_saveexec_b64 s[30:31], s[0:1]
	s_cbranch_execz .LBB0_358
	s_nop 0
	v_add_f32_e32 v20, v18, v19
	s_lshl_b32 s34, s8, 2
	v_lshlrev_b64 v[18:19], 7, v[54:55]
	s_ashr_i32 s35, s34, 31
	v_lshl_add_u64 v[18:19], s[12:13], 0, v[18:19]
	v_lshl_add_u64 v[18:19], s[34:35], 2, v[18:19]
	s_lshl_b32 s40, s72, 2
	v_lshl_add_u64 v[18:19], v[18:19], 0, s[40:41]
	global_store_dword v[18:19], v20, off
.LBB0_358:
	s_or_b64 exec, exec, s[30:31]
	v_add_f32_e32 v10, v10, v102
	v_add_f32_e32 v2, v2, v86
	v_mul_f32_e32 v10, 0xbfb8aa3b, v10
	v_add_f32_e32 v11, v11, v103
	v_mul_f32_e32 v2, 0xbfb8aa3b, v2
	v_add_f32_e32 v3, v3, v87
	v_exp_f32_e32 v10, v10
	v_mul_f32_e32 v11, 0xbfb8aa3b, v11
	v_exp_f32_e32 v2, v2
	v_mul_f32_e32 v3, 0xbfb8aa3b, v3
	v_exp_f32_e32 v11, v11
	v_exp_f32_e32 v3, v3
	v_add_f32_e32 v10, 1.0, v10
	v_add_f32_e32 v12, v12, v104
	v_add_f32_e32 v2, 1.0, v2
	v_add_f32_e32 v4, v4, v88
	v_rcp_f32_e32 v10, v10
	v_add_f32_e32 v11, 1.0, v11
	v_mul_f32_e32 v12, 0xbfb8aa3b, v12
	v_add_f32_e32 v13, v13, v105
	v_rcp_f32_e32 v2, v2
	v_add_f32_e32 v3, 1.0, v3
	v_mul_f32_e32 v4, 0xbfb8aa3b, v4
	v_add_f32_e32 v5, v5, v89
	v_rcp_f32_e32 v11, v11
	v_exp_f32_e32 v12, v12
	v_mul_f32_e32 v13, 0xbfb8aa3b, v13
	v_rcp_f32_e32 v3, v3
	v_exp_f32_e32 v4, v4
	v_mul_f32_e32 v5, 0xbfb8aa3b, v5
	v_exp_f32_e32 v13, v13
	v_exp_f32_e32 v5, v5
	s_waitcnt vmcnt(1)
	v_lshlrev_b32_e32 v18, 16, v34
	v_lshlrev_b32_e32 v22, 16, v36
	v_add_f32_e32 v14, v14, v94
	v_add_f32_e32 v6, v6, v82
	s_waitcnt lgkmcnt(0)
	v_and_b32_e32 v19, 0xffff0000, v34
	v_and_b32_e32 v23, 0xffff0000, v36
	v_fmac_f32_e32 v18, v14, v10
	v_add_f32_e32 v10, v15, v95
	v_fmac_f32_e32 v22, v6, v2
	v_add_f32_e32 v2, v7, v83
	v_fmac_f32_e32 v19, v10, v11
	v_add_f32_e32 v10, 1.0, v12
	v_fmac_f32_e32 v23, v2, v3
	v_add_f32_e32 v2, 1.0, v4
	v_rcp_f32_e32 v10, v10
	v_add_f32_e32 v11, 1.0, v13
	v_rcp_f32_e32 v2, v2
	v_add_f32_e32 v3, 1.0, v5
	v_rcp_f32_e32 v11, v11
	v_rcp_f32_e32 v3, v3
	v_lshlrev_b32_e32 v20, 16, v35
	v_lshlrev_b32_e32 v24, 16, v37
	v_add_f32_e32 v12, v16, v96
	v_add_f32_e32 v4, v8, v84
	v_and_b32_e32 v21, 0xffff0000, v35
	v_and_b32_e32 v25, 0xffff0000, v37
	v_fmac_f32_e32 v20, v12, v10
	v_add_f32_e32 v10, v17, v97
	v_fmac_f32_e32 v24, v4, v2
	v_add_f32_e32 v2, v9, v85
	v_fmac_f32_e32 v21, v10, v11
	v_fmac_f32_e32 v25, v2, v3
	v_mul_f32_e32 v10, v19, v19
	v_mul_f32_e32 v11, v21, v21
	v_mul_f32_e32 v2, v23, v23
	v_mul_f32_e32 v3, v25, v25
	v_fmac_f32_e32 v10, v18, v18
	v_fmac_f32_e32 v11, v20, v20
	v_fmac_f32_e32 v2, v22, v22
	v_fmac_f32_e32 v3, v24, v24
	v_add_f32_e32 v10, v10, v11
	v_add_f32_e32 v2, v2, v3
	v_add_f32_e32 v2, v10, v2
	v_cvt_pk_bf16_f32 v4, v18, v19
	v_cvt_pk_bf16_f32 v5, v20, v21
	s_nop 0
	v_mov_b32_e32 v3, v2
	v_mov_b32_e32 v190, v2
	s_nop 1
	v_permlane16_swap_b32 v3, v190
	v_add_f32_e32 v2, v3, v190
	v_mov_b32_e32 v3, v2
	v_mov_b32_e32 v190, v2
	s_nop 1
	v_permlane32_swap_b32 v190, v3
	v_cvt_pk_bf16_f32 v6, v22, v23
	v_cvt_pk_bf16_f32 v7, v24, v25
	global_store_dwordx4 v[40:41], v[4:7], off
	s_and_saveexec_b64 s[30:31], s[0:1]
	s_cbranch_execz .LBB0_360
	s_nop 0
	v_add_f32_e32 v4, v2, v3
	s_lshl_b32 s34, s8, 2
	v_lshlrev_b64 v[2:3], 7, v[38:39]
	s_ashr_i32 s35, s34, 31
	v_lshl_add_u64 v[2:3], s[12:13], 0, v[2:3]
	v_lshl_add_u64 v[2:3], s[34:35], 2, v[2:3]
	s_lshl_b32 s40, s72, 2
	v_lshl_add_u64 v[2:3], v[2:3], 0, s[40:41]
	global_store_dword v[2:3], v4, off

.LBB0_534:
	s_add_u32 s24, s22, 0xfff00080
	s_addc_u32 s25, s23, -1
	s_add_i32 s56, 0, 0x10000
	s_cmp_eq_u32 s69, 60
	s_cselect_b32 s27, s13, s25
	s_cselect_b32 s26, s19, s24
	v_add_u32_e32 v152, s56, v159
	s_cselect_b32 s25, s11, s68
	s_cselect_b32 s24, s21, s40
	s_add_i32 s70, 0, 0x14000
	ds_read_b128 v[130:133], v152
	ds_read_b128 v[134:137], v152 offset:1024
	ds_read_b128 v[148:151], v152 offset:2048
	ds_read_b128 v[162:165], v152 offset:3072
	v_add_u32_e32 v152, s70, v159
	ds_read_b128 v[166:169], v152
	ds_read_b128 v[170:173], v152 offset:1024
	ds_read_b128 v[174:177], v152 offset:2048
	ds_read_b128 v[178:181], v152 offset:3072
	v_lshl_add_u64 v[152:153], s[22:23], 0, v[144:145]
	s_add_i32 m0, s38, 0xc000
	ds_read_b128 v[182:185], v161
	ds_read_b128 v[186:189], v161 offset:1024
	ds_read_b128 v[190:193], v161 offset:2048
	ds_read_b128 v[194:197], v161 offset:3072
	ds_read_b128 v[198:201], v161 offset:4096
	ds_read_b128 v[202:205], v161 offset:5120
	ds_read_b128 v[206:209], v161 offset:6144
	ds_read_b128 v[210:213], v161 offset:7168
	global_load_lds_dwordx4 v[152:153], off
	v_lshl_add_u64 v[152:153], s[22:23], 0, v[146:147]
	s_add_i32 m0, s38, 0xe000
	s_nop 0
	global_load_lds_dwordx4 v[152:153], off
	s_waitcnt vmcnt(8)
	s_waitcnt lgkmcnt(0)
	s_barrier
	s_waitcnt lgkmcnt(0)
	v_mfma_f32_16x16x32_bf16 v[126:129], v[130:133], v[182:185], v[126:129]
	v_mfma_f32_16x16x32_bf16 v[122:125], v[148:151], v[182:185], v[122:125]
	v_mfma_f32_16x16x32_bf16 v[110:113], v[130:133], v[190:193], v[110:113]
	v_mfma_f32_16x16x32_bf16 v[106:109], v[148:151], v[190:193], v[106:109]
	v_mfma_f32_16x16x32_bf16 v[94:97], v[130:133], v[198:201], v[94:97]
	v_mfma_f32_16x16x32_bf16 v[90:93], v[148:151], v[198:201], v[90:93]
	v_mfma_f32_16x16x32_bf16 v[78:81], v[130:133], v[206:209], v[78:81]
	v_mfma_f32_16x16x32_bf16 v[74:77], v[148:151], v[206:209], v[74:77]
	v_mfma_f32_16x16x32_bf16 v[126:129], v[134:137], v[186:189], v[126:129]
	v_mfma_f32_16x16x32_bf16 v[122:125], v[162:165], v[186:189], v[122:125]
	v_mfma_f32_16x16x32_bf16 v[110:113], v[134:137], v[194:197], v[110:113]
	v_mfma_f32_16x16x32_bf16 v[106:109], v[162:165], v[194:197], v[106:109]
	v_mfma_f32_16x16x32_bf16 v[94:97], v[134:137], v[202:205], v[94:97]
	v_mfma_f32_16x16x32_bf16 v[90:93], v[162:165], v[202:205], v[90:93]
	v_mfma_f32_16x16x32_bf16 v[78:81], v[134:137], v[210:213], v[78:81]
	v_mfma_f32_16x16x32_bf16 v[74:77], v[162:165], v[210:213], v[74:77]
	v_mfma_f32_16x16x32_bf16 v[118:121], v[166:169], v[182:185], v[118:121]
	v_mfma_f32_16x16x32_bf16 v[114:117], v[174:177], v[182:185], v[114:117]
	v_mfma_f32_16x16x32_bf16 v[102:105], v[166:169], v[190:193], v[102:105]
	v_mfma_f32_16x16x32_bf16 v[98:101], v[174:177], v[190:193], v[98:101]
	v_mfma_f32_16x16x32_bf16 v[86:89], v[166:169], v[198:201], v[86:89]
	v_mfma_f32_16x16x32_bf16 v[82:85], v[174:177], v[198:201], v[82:85]
	v_mfma_f32_16x16x32_bf16 v[70:73], v[166:169], v[206:209], v[70:73]
	v_mfma_f32_16x16x32_bf16 v[66:69], v[174:177], v[206:209], v[66:69]
	v_mfma_f32_16x16x32_bf16 v[118:121], v[170:173], v[186:189], v[118:121]
	v_mfma_f32_16x16x32_bf16 v[114:117], v[178:181], v[186:189], v[114:117]
	v_mfma_f32_16x16x32_bf16 v[102:105], v[170:173], v[194:197], v[102:105]
	v_mfma_f32_16x16x32_bf16 v[98:101], v[178:181], v[194:197], v[98:101]
	v_mfma_f32_16x16x32_bf16 v[86:89], v[170:173], v[202:205], v[86:89]
	v_mfma_f32_16x16x32_bf16 v[82:85], v[178:181], v[202:205], v[82:85]
	v_mfma_f32_16x16x32_bf16 v[70:73], v[170:173], v[210:213], v[70:73]
	v_mfma_f32_16x16x32_bf16 v[66:69], v[178:181], v[210:213], v[66:69]
	s_barrier
	s_add_i32 s56, s56, s37
	v_lshl_add_u64 v[152:153], s[24:25], 0, v[154:155]
	s_mov_b32 m0, s56
	ds_read_b128 v[182:185], v161 offset:16384
	ds_read_b128 v[186:189], v161 offset:17408
	ds_read_b128 v[190:193], v161 offset:18432
	ds_read_b128 v[194:197], v161 offset:19456
	ds_read_b128 v[198:201], v161 offset:20480
	ds_read_b128 v[202:205], v161 offset:21504
	ds_read_b128 v[206:209], v161 offset:22528
	ds_read_b128 v[210:213], v161 offset:23552
	global_load_lds_dwordx4 v[152:153], off
	s_add_i32 m0, s56, 0x2000
	s_add_u32 s56, s24, 0x100000
	v_lshl_add_u64 v[156:157], s[24:25], 0, v[142:143]
	s_addc_u32 s57, s25, 0
	s_add_i32 s70, s70, s37
	global_load_lds_dwordx4 v[156:157], off
	v_lshl_add_u64 v[214:215], s[56:57], 0, v[154:155]
	s_mov_b32 m0, s70
	v_lshl_add_u64 v[216:217], s[26:27], 0, v[140:141]
	global_load_lds_dwordx4 v[214:215], off
	v_lshl_add_u64 v[214:215], s[56:57], 0, v[142:143]
	s_add_i32 m0, s70, 0x2000
	s_nop 0
	global_load_lds_dwordx4 v[214:215], off
	v_lshl_add_u64 v[214:215], s[26:27], 0, v[138:139]
	s_mov_b32 m0, s38
	s_nop 0
	global_load_lds_dwordx4 v[214:215], off
	s_mov_b32 m0, s39
	s_nop 0
	global_load_lds_dwordx4 v[216:217], off
	s_waitcnt vmcnt(8)
	s_waitcnt lgkmcnt(0)
	s_barrier
	s_waitcnt lgkmcnt(0)
	v_mfma_f32_16x16x32_bf16 v[62:65], v[130:133], v[182:185], v[62:65]
	v_mfma_f32_16x16x32_bf16 v[58:61], v[148:151], v[182:185], v[58:61]
	v_mfma_f32_16x16x32_bf16 v[46:49], v[130:133], v[190:193], v[46:49]
	v_mfma_f32_16x16x32_bf16 v[42:45], v[148:151], v[190:193], v[42:45]
	v_mfma_f32_16x16x32_bf16 v[30:33], v[130:133], v[198:201], v[30:33]
	v_mfma_f32_16x16x32_bf16 v[26:29], v[148:151], v[198:201], v[26:29]
	v_mfma_f32_16x16x32_bf16 v[14:17], v[130:133], v[206:209], v[14:17]
	v_mfma_f32_16x16x32_bf16 v[10:13], v[148:151], v[206:209], v[10:13]
	v_mfma_f32_16x16x32_bf16 v[62:65], v[134:137], v[186:189], v[62:65]
	v_mfma_f32_16x16x32_bf16 v[58:61], v[162:165], v[186:189], v[58:61]
	v_mfma_f32_16x16x32_bf16 v[46:49], v[134:137], v[194:197], v[46:49]
	v_mfma_f32_16x16x32_bf16 v[42:45], v[162:165], v[194:197], v[42:45]
	v_mfma_f32_16x16x32_bf16 v[30:33], v[134:137], v[202:205], v[30:33]
	v_mfma_f32_16x16x32_bf16 v[26:29], v[162:165], v[202:205], v[26:29]
	v_mfma_f32_16x16x32_bf16 v[14:17], v[134:137], v[210:213], v[14:17]
	v_mfma_f32_16x16x32_bf16 v[10:13], v[162:165], v[210:213], v[10:13]
	v_mfma_f32_16x16x32_bf16 v[54:57], v[166:169], v[182:185], v[54:57]
	v_mfma_f32_16x16x32_bf16 v[50:53], v[174:177], v[182:185], v[50:53]
	v_mfma_f32_16x16x32_bf16 v[38:41], v[166:169], v[190:193], v[38:41]
	v_mfma_f32_16x16x32_bf16 v[34:37], v[174:177], v[190:193], v[34:37]
	v_mfma_f32_16x16x32_bf16 v[22:25], v[166:169], v[198:201], v[22:25]
	v_mfma_f32_16x16x32_bf16 v[18:21], v[174:177], v[198:201], v[18:21]
	v_mfma_f32_16x16x32_bf16 v[6:9], v[166:169], v[206:209], v[6:9]
	v_mfma_f32_16x16x32_bf16 v[2:5], v[174:177], v[206:209], v[2:5]
	v_mfma_f32_16x16x32_bf16 v[54:57], v[170:173], v[186:189], v[54:57]
	v_mfma_f32_16x16x32_bf16 v[50:53], v[178:181], v[186:189], v[50:53]
	v_mfma_f32_16x16x32_bf16 v[38:41], v[170:173], v[194:197], v[38:41]
	v_mfma_f32_16x16x32_bf16 v[34:37], v[178:181], v[194:197], v[34:37]
	v_mfma_f32_16x16x32_bf16 v[22:25], v[170:173], v[202:205], v[22:25]
	v_mfma_f32_16x16x32_bf16 v[18:21], v[178:181], v[202:205], v[18:21]
	v_mfma_f32_16x16x32_bf16 v[6:9], v[170:173], v[210:213], v[6:9]
	v_mfma_f32_16x16x32_bf16 v[2:5], v[178:181], v[210:213], v[2:5]
	s_barrier
	s_add_i32 s56, 0, 0x18000
	s_add_i32 s57, 0, 0x1c000
	v_add_u32_e32 v162, s56, v159
	v_add_u32_e32 v178, s57, v159
	ds_read_b128 v[130:133], v162
	ds_read_b128 v[134:137], v162 offset:1024
	ds_read_b128 v[148:151], v162 offset:2048
	ds_read_b128 v[162:165], v162 offset:3072
	ds_read_b128 v[166:169], v178
	ds_read_b128 v[170:173], v178 offset:1024
	ds_read_b128 v[174:177], v178 offset:2048
	ds_read_b128 v[178:181], v178 offset:3072
	s_add_u32 s26, s26, 0x100000
	s_addc_u32 s27, s27, 0
	s_mov_b32 m0, s44
	v_lshl_add_u64 v[218:219], s[26:27], 0, v[138:139]
	ds_read_b128 v[182:185], v161 offset:32768
	ds_read_b128 v[186:189], v161 offset:33792
	ds_read_b128 v[190:193], v161 offset:34816
	ds_read_b128 v[194:197], v161 offset:35840
	ds_read_b128 v[198:201], v161 offset:36864
	ds_read_b128 v[202:205], v161 offset:37888
	ds_read_b128 v[206:209], v161 offset:38912
	ds_read_b128 v[210:213], v161 offset:39936
	global_load_lds_dwordx4 v[218:219], off
	v_lshl_add_u64 v[218:219], s[26:27], 0, v[140:141]
	s_mov_b32 m0, s45
	s_nop 0
	global_load_lds_dwordx4 v[218:219], off
	s_waitcnt vmcnt(8)
	s_waitcnt lgkmcnt(0)
	s_barrier
	s_waitcnt lgkmcnt(0)
	v_mfma_f32_16x16x32_bf16 v[126:129], v[130:133], v[182:185], v[126:129]
	v_mfma_f32_16x16x32_bf16 v[122:125], v[148:151], v[182:185], v[122:125]
	v_mfma_f32_16x16x32_bf16 v[110:113], v[130:133], v[190:193], v[110:113]
	v_mfma_f32_16x16x32_bf16 v[106:109], v[148:151], v[190:193], v[106:109]
	v_mfma_f32_16x16x32_bf16 v[94:97], v[130:133], v[198:201], v[94:97]
	v_mfma_f32_16x16x32_bf16 v[90:93], v[148:151], v[198:201], v[90:93]
	v_mfma_f32_16x16x32_bf16 v[78:81], v[130:133], v[206:209], v[78:81]
	v_mfma_f32_16x16x32_bf16 v[74:77], v[148:151], v[206:209], v[74:77]
	v_mfma_f32_16x16x32_bf16 v[126:129], v[134:137], v[186:189], v[126:129]
	v_mfma_f32_16x16x32_bf16 v[122:125], v[162:165], v[186:189], v[122:125]
	v_mfma_f32_16x16x32_bf16 v[110:113], v[134:137], v[194:197], v[110:113]
	v_mfma_f32_16x16x32_bf16 v[106:109], v[162:165], v[194:197], v[106:109]
	v_mfma_f32_16x16x32_bf16 v[94:97], v[134:137], v[202:205], v[94:97]
	v_mfma_f32_16x16x32_bf16 v[90:93], v[162:165], v[202:205], v[90:93]
	v_mfma_f32_16x16x32_bf16 v[78:81], v[134:137], v[210:213], v[78:81]
	v_mfma_f32_16x16x32_bf16 v[74:77], v[162:165], v[210:213], v[74:77]
	v_mfma_f32_16x16x32_bf16 v[118:121], v[166:169], v[182:185], v[118:121]
	v_mfma_f32_16x16x32_bf16 v[114:117], v[174:177], v[182:185], v[114:117]
	v_mfma_f32_16x16x32_bf16 v[102:105], v[166:169], v[190:193], v[102:105]
	v_mfma_f32_16x16x32_bf16 v[98:101], v[174:177], v[190:193], v[98:101]
	v_mfma_f32_16x16x32_bf16 v[86:89], v[166:169], v[198:201], v[86:89]
	v_mfma_f32_16x16x32_bf16 v[82:85], v[174:177], v[198:201], v[82:85]
	v_mfma_f32_16x16x32_bf16 v[70:73], v[166:169], v[206:209], v[70:73]
	v_mfma_f32_16x16x32_bf16 v[66:69], v[174:177], v[206:209], v[66:69]
	v_mfma_f32_16x16x32_bf16 v[118:121], v[170:173], v[186:189], v[118:121]
	v_mfma_f32_16x16x32_bf16 v[114:117], v[178:181], v[186:189], v[114:117]
	v_mfma_f32_16x16x32_bf16 v[102:105], v[170:173], v[194:197], v[102:105]
	v_mfma_f32_16x16x32_bf16 v[98:101], v[178:181], v[194:197], v[98:101]
	v_mfma_f32_16x16x32_bf16 v[86:89], v[170:173], v[202:205], v[86:89]
	v_mfma_f32_16x16x32_bf16 v[82:85], v[178:181], v[202:205], v[82:85]
	v_mfma_f32_16x16x32_bf16 v[70:73], v[170:173], v[210:213], v[70:73]
	v_mfma_f32_16x16x32_bf16 v[66:69], v[178:181], v[210:213], v[66:69]
	s_barrier
	s_add_i32 s26, s56, s37
	v_lshl_add_u64 v[152:153], v[152:153], 0, s[62:63]
	s_mov_b32 m0, s26
	ds_read_b128 v[182:185], v161 offset:49152
	ds_read_b128 v[186:189], v161 offset:50176
	ds_read_b128 v[190:193], v161 offset:51200
	ds_read_b128 v[194:197], v161 offset:52224
	ds_read_b128 v[198:201], v161 offset:53248
	ds_read_b128 v[202:205], v161 offset:54272
	ds_read_b128 v[206:209], v161 offset:55296
	ds_read_b128 v[210:213], v161 offset:56320
	global_load_lds_dwordx4 v[152:153], off
	s_add_i32 m0, s26, 0x2000
	s_add_u32 s24, s24, 0x100080
	v_lshl_add_u64 v[152:153], v[156:157], 0, s[62:63]
	s_addc_u32 s25, s25, 0
	s_add_i32 s26, s57, s37
	global_load_lds_dwordx4 v[152:153], off
	v_lshl_add_u64 v[152:153], s[24:25], 0, v[154:155]
	s_mov_b32 m0, s26
	s_nop 0
	global_load_lds_dwordx4 v[152:153], off
	v_lshl_add_u64 v[152:153], s[24:25], 0, v[142:143]
	s_add_i32 m0, s26, 0x2000
	s_nop 0
	global_load_lds_dwordx4 v[152:153], off
	v_lshl_add_u64 v[152:153], v[214:215], 0, s[62:63]
	s_mov_b32 m0, s53
	s_nop 0
	global_load_lds_dwordx4 v[152:153], off
	v_lshl_add_u64 v[152:153], v[216:217], 0, s[62:63]
	s_mov_b32 m0, s55
	s_nop 0
	global_load_lds_dwordx4 v[152:153], off
	s_waitcnt vmcnt(8)
	s_waitcnt lgkmcnt(0)
	s_barrier
	s_waitcnt lgkmcnt(0)
	v_mfma_f32_16x16x32_bf16 v[62:65], v[130:133], v[182:185], v[62:65]
	v_mfma_f32_16x16x32_bf16 v[58:61], v[148:151], v[182:185], v[58:61]
	v_mfma_f32_16x16x32_bf16 v[46:49], v[130:133], v[190:193], v[46:49]
	v_mfma_f32_16x16x32_bf16 v[42:45], v[148:151], v[190:193], v[42:45]
	v_mfma_f32_16x16x32_bf16 v[30:33], v[130:133], v[198:201], v[30:33]
	v_mfma_f32_16x16x32_bf16 v[26:29], v[148:151], v[198:201], v[26:29]
	v_mfma_f32_16x16x32_bf16 v[14:17], v[130:133], v[206:209], v[14:17]
	v_mfma_f32_16x16x32_bf16 v[10:13], v[148:151], v[206:209], v[10:13]
	v_mfma_f32_16x16x32_bf16 v[62:65], v[134:137], v[186:189], v[62:65]
	v_mfma_f32_16x16x32_bf16 v[58:61], v[162:165], v[186:189], v[58:61]
	v_mfma_f32_16x16x32_bf16 v[46:49], v[134:137], v[194:197], v[46:49]
	v_mfma_f32_16x16x32_bf16 v[42:45], v[162:165], v[194:197], v[42:45]
	v_mfma_f32_16x16x32_bf16 v[30:33], v[134:137], v[202:205], v[30:33]
	v_mfma_f32_16x16x32_bf16 v[26:29], v[162:165], v[202:205], v[26:29]
	v_mfma_f32_16x16x32_bf16 v[14:17], v[134:137], v[210:213], v[14:17]
	v_mfma_f32_16x16x32_bf16 v[10:13], v[162:165], v[210:213], v[10:13]
	v_mfma_f32_16x16x32_bf16 v[54:57], v[166:169], v[182:185], v[54:57]
	v_mfma_f32_16x16x32_bf16 v[50:53], v[174:177], v[182:185], v[50:53]
	v_mfma_f32_16x16x32_bf16 v[38:41], v[166:169], v[190:193], v[38:41]
	v_mfma_f32_16x16x32_bf16 v[34:37], v[174:177], v[190:193], v[34:37]
	v_mfma_f32_16x16x32_bf16 v[22:25], v[166:169], v[198:201], v[22:25]
	v_mfma_f32_16x16x32_bf16 v[18:21], v[174:177], v[198:201], v[18:21]
	v_mfma_f32_16x16x32_bf16 v[6:9], v[166:169], v[206:209], v[6:9]
	v_mfma_f32_16x16x32_bf16 v[2:5], v[174:177], v[206:209], v[2:5]
	v_mfma_f32_16x16x32_bf16 v[54:57], v[170:173], v[186:189], v[54:57]
	v_mfma_f32_16x16x32_bf16 v[50:53], v[178:181], v[186:189], v[50:53]
	v_mfma_f32_16x16x32_bf16 v[38:41], v[170:173], v[194:197], v[38:41]
	v_mfma_f32_16x16x32_bf16 v[34:37], v[178:181], v[194:197], v[34:37]
	v_mfma_f32_16x16x32_bf16 v[22:25], v[170:173], v[202:205], v[22:25]
	v_mfma_f32_16x16x32_bf16 v[18:21], v[178:181], v[202:205], v[18:21]
	v_mfma_f32_16x16x32_bf16 v[6:9], v[170:173], v[210:213], v[6:9]
	v_mfma_f32_16x16x32_bf16 v[2:5], v[178:181], v[210:213], v[2:5]
	s_barrier
	s_add_i32 s69, s69, 2
	s_add_u32 s22, s22, 0x100
	s_addc_u32 s23, s23, 0
	s_add_u32 s40, s40, 0x100
	s_addc_u32 s68, s68, 0
	s_cmp_gt_u32 s69, 61
	s_cbranch_scc0 .LBB0_534
	v_lshl_add_u32 v148, s20, 8, v158
	v_lshl_or_b32 v150, s18, 8, v160
	v_ashrrev_i32_e32 v149, 31, v148
	v_lshlrev_b64 v[130:131], 11, v[148:149]
	v_ashrrev_i32_e32 v151, 31, v150
	v_lshl_add_u64 v[130:131], s[8:9], 0, v[130:131]
	v_lshlrev_b64 v[132:133], 1, v[150:151]
	v_lshl_add_u64 v[172:173], v[130:131], 0, v[132:133]
	global_load_dwordx4 v[164:167], v[172:173], off
	global_load_dwordx4 v[168:171], v[172:173], off offset:256
	v_or_b32_e32 v152, 16, v148
	v_ashrrev_i32_e32 v153, 31, v152
	v_lshlrev_b64 v[130:131], 11, v[152:153]
	v_lshl_add_u64 v[130:131], s[8:9], 0, v[130:131]
	v_lshl_add_u64 v[156:157], v[130:131], 0, v[132:133]
	global_load_dwordx4 v[134:137], v[156:157], off
	global_load_dwordx4 v[130:133], v[156:157], off offset:256
	v_and_b32_e32 v163, 64, v1
	v_xor_b32_e32 v162, 16, v1
	v_add_u32_e32 v163, 64, v163
	v_xor_b32_e32 v174, 32, v1
	v_cmp_lt_i32_e32 vcc, v162, v163
	s_lshl_b32 s18, s18, 2
	s_ashr_i32 s19, s18, 31
	v_cndmask_b32_e32 v162, v1, v162, vcc
	v_cmp_lt_i32_e32 vcc, v174, v163
	v_lshlrev_b32_e32 v162, 2, v162
	s_waitcnt vmcnt(0)
	v_and_b32_e32 v175, 0xffff0000, v164
	v_cndmask_b32_e32 v163, v1, v174, vcc
	v_lshlrev_b32_e32 v174, 16, v164
	v_lshlrev_b32_e32 v164, 16, v165
	v_and_b32_e32 v165, 0xffff0000, v165
	v_lshlrev_b32_e32 v176, 16, v166
	v_and_b32_e32 v177, 0xffff0000, v166
	v_lshlrev_b32_e32 v166, 16, v167
	v_and_b32_e32 v167, 0xffff0000, v167
	v_lshlrev_b32_e32 v178, 16, v168
	v_and_b32_e32 v179, 0xffff0000, v168
	v_lshlrev_b32_e32 v168, 16, v169
	v_and_b32_e32 v169, 0xffff0000, v169
	v_lshlrev_b32_e32 v180, 16, v170
	v_and_b32_e32 v181, 0xffff0000, v170
	v_lshlrev_b32_e32 v170, 16, v171
	v_and_b32_e32 v171, 0xffff0000, v171
	v_pk_add_f32 v[128:129], v[128:129], v[164:165]
	v_pk_add_f32 v[126:127], v[126:127], v[174:175]
	v_pk_add_f32 v[122:123], v[122:123], v[176:177]
	v_pk_add_f32 v[124:125], v[124:125], v[166:167]
	v_pk_add_f32 v[120:121], v[120:121], v[168:169]
	v_pk_add_f32 v[118:119], v[118:119], v[178:179]
	v_pk_add_f32 v[164:165], v[114:115], v[180:181]
	v_pk_add_f32 v[166:167], v[116:117], v[170:171]
	v_cvt_pk_bf16_f32 v114, v126, v127
	v_cvt_pk_bf16_f32 v115, v128, v129
	v_mul_f32_e32 v116, v126, v126
	v_mul_f32_e32 v117, v128, v128
	v_mul_f32_e32 v126, v122, v122
	v_mul_f32_e32 v128, v125, v125
	v_mul_f32_e32 v168, v118, v118
	v_mul_f32_e32 v169, v120, v120
	v_mul_f32_e32 v170, v164, v164
	v_mul_f32_e32 v171, v167, v167
	v_fmac_f32_e32 v116, v127, v127
	v_fmac_f32_e32 v117, v129, v129
	v_fmac_f32_e32 v126, v123, v123
	v_fmac_f32_e32 v128, v124, v124
	v_fmac_f32_e32 v168, v119, v119
	v_fmac_f32_e32 v169, v121, v121
	v_fmac_f32_e32 v170, v165, v165
	v_fmac_f32_e32 v171, v166, v166
	v_add_f32_e32 v116, v117, v116
	v_add_f32_e32 v117, v128, v126
	v_add_f32_e32 v126, v169, v168
	v_add_f32_e32 v127, v171, v170
	v_add_f32_e32 v116, v117, v116
	v_add_f32_e32 v117, v127, v126
	v_add_f32_e32 v126, v116, v117
	v_cvt_pk_bf16_f32 v116, v122, v123
	v_cvt_pk_bf16_f32 v117, v124, v125
	global_store_dwordx4 v[172:173], v[114:117], off
	s_nop 0
	s_nop 0
	v_mov_b32_e32 v127, v126
	v_mov_b32_e32 v190, v126
	s_nop 1
	v_permlane16_swap_b32 v127, v190
	v_add_f32_e32 v114, v127, v190
	v_lshlrev_b32_e32 v126, 2, v163
	v_mov_b32_e32 v115, v114
	v_mov_b32_e32 v190, v114
	s_nop 1
	v_permlane32_swap_b32 v190, v115
	v_cvt_pk_bf16_f32 v116, v118, v119
	v_cvt_pk_bf16_f32 v117, v120, v121
	v_cvt_pk_bf16_f32 v118, v164, v165
	v_cvt_pk_bf16_f32 v119, v166, v167
	global_store_dwordx4 v[172:173], v[116:119], off offset:256
	s_and_saveexec_b64 s[20:21], s[0:1]
	s_cbranch_execz .LBB0_537
	v_lshlrev_b64 v[116:117], 7, v[148:149]
	v_lshl_add_u64 v[116:117], s[6:7], 0, v[116:117]
	v_lshl_add_u64 v[116:117], s[18:19], 2, v[116:117]
	s_lshl_b32 s40, s51, 2
	v_lshl_add_u64 v[116:117], v[116:117], 0, s[40:41]
	s_nop 0
	v_add_f32_e32 v114, v114, v115
	global_store_dword v[116:117], v114, off
.LBB0_537:
	s_or_b64 exec, exec, s[20:21]
	v_or_b32_e32 v122, 32, v148
	v_ashrrev_i32_e32 v123, 31, v122
	s_waitcnt lgkmcnt(0)
	v_lshlrev_b64 v[114:115], 11, v[122:123]
	v_lshl_add_u64 v[114:115], s[8:9], 0, v[114:115]
	v_lshl_add_u64 v[124:125], v[150:151], 1, v[114:115]
	global_load_dwordx4 v[118:121], v[124:125], off
	global_load_dwordx4 v[114:117], v[124:125], off offset:256
	v_lshlrev_b32_e32 v128, 16, v134
	v_and_b32_e32 v129, 0xffff0000, v134
	v_lshlrev_b32_e32 v134, 16, v135
	v_and_b32_e32 v135, 0xffff0000, v135
	v_pk_add_f32 v[112:113], v[112:113], v[134:135]
	v_pk_add_f32 v[110:111], v[110:111], v[128:129]
	v_lshlrev_b32_e32 v134, 16, v137
	v_and_b32_e32 v135, 0xffff0000, v137
	v_lshlrev_b32_e32 v128, 16, v136
	v_and_b32_e32 v129, 0xffff0000, v136
	v_pk_add_f32 v[134:135], v[108:109], v[134:135]
	v_mul_f32_e32 v108, v110, v110
	v_mul_f32_e32 v109, v112, v112
	v_pk_add_f32 v[128:129], v[106:107], v[128:129]
	v_fmac_f32_e32 v108, v111, v111
	v_fmac_f32_e32 v109, v113, v113
	v_cvt_pk_bf16_f32 v106, v110, v111
	v_add_f32_e32 v108, v109, v108
	v_mul_f32_e32 v109, v128, v128
	v_mul_f32_e32 v110, v135, v135
	v_fmac_f32_e32 v109, v129, v129
	v_fmac_f32_e32 v110, v134, v134
	v_add_f32_e32 v109, v110, v109
	v_add_f32_e32 v127, v109, v108
	v_lshlrev_b32_e32 v108, 16, v130
	v_and_b32_e32 v109, 0xffff0000, v130
	v_lshlrev_b32_e32 v110, 16, v131
	v_and_b32_e32 v111, 0xffff0000, v131
	v_pk_add_f32 v[104:105], v[104:105], v[110:111]
	v_pk_add_f32 v[102:103], v[102:103], v[108:109]
	v_lshlrev_b32_e32 v108, 16, v132
	v_and_b32_e32 v109, 0xffff0000, v132
	v_cvt_pk_bf16_f32 v107, v112, v113
	v_lshlrev_b32_e32 v110, 16, v133
	v_and_b32_e32 v111, 0xffff0000, v133
	v_pk_add_f32 v[112:113], v[98:99], v[108:109]
	v_mul_f32_e32 v98, v102, v102
	v_mul_f32_e32 v99, v104, v104
	v_pk_add_f32 v[110:111], v[100:101], v[110:111]
	v_fmac_f32_e32 v98, v103, v103
	v_fmac_f32_e32 v99, v105, v105
	v_add_f32_e32 v98, v99, v98
	v_mul_f32_e32 v99, v112, v112
	v_mul_f32_e32 v100, v111, v111
	v_fmac_f32_e32 v99, v113, v113
	v_fmac_f32_e32 v100, v110, v110
	v_add_f32_e32 v99, v100, v99
	v_add_f32_e32 v98, v99, v98
	v_add_f32_e32 v98, v127, v98
	v_cvt_pk_bf16_f32 v108, v128, v129
	v_cvt_pk_bf16_f32 v109, v134, v135
	global_store_dwordx4 v[156:157], v[106:109], off
	v_cvt_pk_bf16_f32 v100, v102, v103
	s_nop 0
	v_mov_b32_e32 v99, v98
	v_mov_b32_e32 v190, v98
	s_nop 1
	v_permlane16_swap_b32 v99, v190
	v_add_f32_e32 v98, v99, v190
	v_mov_b32_e32 v99, v98
	v_mov_b32_e32 v190, v98
	s_nop 1
	v_permlane32_swap_b32 v190, v99
	v_cvt_pk_bf16_f32 v101, v104, v105
	v_cvt_pk_bf16_f32 v102, v112, v113
	v_cvt_pk_bf16_f32 v103, v110, v111
	global_store_dwordx4 v[156:157], v[100:103], off offset:256
	s_and_saveexec_b64 s[20:21], s[0:1]
	s_cbranch_execz .LBB0_539
	v_lshlrev_b64 v[100:101], 7, v[152:153]
	v_lshl_add_u64 v[100:101], s[6:7], 0, v[100:101]
	v_lshl_add_u64 v[100:101], s[18:19], 2, v[100:101]
	s_lshl_b32 s40, s51, 2
	v_lshl_add_u64 v[100:101], v[100:101], 0, s[40:41]
	s_nop 0
	v_add_f32_e32 v98, v98, v99
	global_store_dword v[100:101], v98, off
.LBB0_539:
	s_or_b64 exec, exec, s[20:21]
	v_or_b32_e32 v106, 48, v148
	v_ashrrev_i32_e32 v107, 31, v106
	s_waitcnt lgkmcnt(0)
	v_lshlrev_b64 v[98:99], 11, v[106:107]
	v_lshl_add_u64 v[98:99], s[8:9], 0, v[98:99]
	v_lshl_add_u64 v[108:109], v[150:151], 1, v[98:99]
	global_load_dwordx4 v[102:105], v[108:109], off
	global_load_dwordx4 v[98:101], v[108:109], off offset:256
	s_waitcnt vmcnt(5)
	v_lshlrev_b32_e32 v110, 16, v118
	v_and_b32_e32 v111, 0xffff0000, v118
	v_lshlrev_b32_e32 v112, 16, v119
	v_and_b32_e32 v113, 0xffff0000, v119
	v_pk_add_f32 v[96:97], v[96:97], v[112:113]
	v_pk_add_f32 v[94:95], v[94:95], v[110:111]
	v_lshlrev_b32_e32 v112, 16, v121
	v_and_b32_e32 v113, 0xffff0000, v121
	v_lshlrev_b32_e32 v110, 16, v120
	v_and_b32_e32 v111, 0xffff0000, v120
	v_pk_add_f32 v[112:113], v[92:93], v[112:113]
	v_mul_f32_e32 v92, v94, v94
	v_mul_f32_e32 v93, v96, v96
	v_pk_add_f32 v[110:111], v[90:91], v[110:111]
	v_fmac_f32_e32 v92, v95, v95
	v_fmac_f32_e32 v93, v97, v97
	v_cvt_pk_bf16_f32 v90, v94, v95
	v_add_f32_e32 v92, v93, v92
	v_mul_f32_e32 v93, v110, v110
	v_mul_f32_e32 v94, v113, v113
	v_fmac_f32_e32 v93, v111, v111
	v_fmac_f32_e32 v94, v112, v112
	v_add_f32_e32 v93, v94, v93
	v_add_f32_e32 v118, v93, v92
	s_waitcnt vmcnt(4)
	v_lshlrev_b32_e32 v92, 16, v114
	v_and_b32_e32 v93, 0xffff0000, v114
	v_lshlrev_b32_e32 v94, 16, v115
	v_and_b32_e32 v95, 0xffff0000, v115
	v_pk_add_f32 v[88:89], v[88:89], v[94:95]
	v_pk_add_f32 v[86:87], v[86:87], v[92:93]
	v_lshlrev_b32_e32 v92, 16, v116
	v_and_b32_e32 v93, 0xffff0000, v116
	v_cvt_pk_bf16_f32 v91, v96, v97
	v_lshlrev_b32_e32 v94, 16, v117
	v_and_b32_e32 v95, 0xffff0000, v117
	v_pk_add_f32 v[96:97], v[82:83], v[92:93]
	v_mul_f32_e32 v82, v86, v86
	v_mul_f32_e32 v83, v88, v88
	v_pk_add_f32 v[94:95], v[84:85], v[94:95]
	v_fmac_f32_e32 v82, v87, v87
	v_fmac_f32_e32 v83, v89, v89
	v_add_f32_e32 v82, v83, v82
	v_mul_f32_e32 v83, v96, v96
	v_mul_f32_e32 v84, v95, v95
	v_fmac_f32_e32 v83, v97, v97
	v_fmac_f32_e32 v84, v94, v94
	v_add_f32_e32 v83, v84, v83
	v_add_f32_e32 v82, v83, v82
	v_add_f32_e32 v82, v118, v82
	v_cvt_pk_bf16_f32 v92, v110, v111
	v_cvt_pk_bf16_f32 v93, v112, v113
	global_store_dwordx4 v[124:125], v[90:93], off
	v_cvt_pk_bf16_f32 v84, v86, v87
	s_nop 0
	v_mov_b32_e32 v83, v82
	v_mov_b32_e32 v190, v82
	s_nop 1
	v_permlane16_swap_b32 v83, v190
	v_add_f32_e32 v82, v83, v190
	v_mov_b32_e32 v83, v82
	v_mov_b32_e32 v190, v82
	s_nop 1
	v_permlane32_swap_b32 v190, v83
	v_cvt_pk_bf16_f32 v85, v88, v89
	v_cvt_pk_bf16_f32 v86, v96, v97
	v_cvt_pk_bf16_f32 v87, v94, v95
	global_store_dwordx4 v[124:125], v[84:87], off offset:256
	s_and_saveexec_b64 s[20:21], s[0:1]
	s_cbranch_execz .LBB0_541
	v_lshlrev_b64 v[84:85], 7, v[122:123]
	v_lshl_add_u64 v[84:85], s[6:7], 0, v[84:85]
	v_lshl_add_u64 v[84:85], s[18:19], 2, v[84:85]
	s_lshl_b32 s40, s51, 2
	v_lshl_add_u64 v[84:85], v[84:85], 0, s[40:41]
	s_nop 0
	v_add_f32_e32 v82, v82, v83
	global_store_dword v[84:85], v82, off
.LBB0_541:
	s_or_b64 exec, exec, s[20:21]
	v_add_u32_e32 v90, 0x80, v148
	v_ashrrev_i32_e32 v91, 31, v90
	s_waitcnt lgkmcnt(0)
	v_lshlrev_b64 v[82:83], 11, v[90:91]
	v_lshl_add_u64 v[82:83], s[8:9], 0, v[82:83]
	v_lshl_add_u64 v[92:93], v[150:151], 1, v[82:83]
	global_load_dwordx4 v[86:89], v[92:93], off
	global_load_dwordx4 v[82:85], v[92:93], off offset:256
	s_waitcnt vmcnt(5)
	v_lshlrev_b32_e32 v94, 16, v102
	v_and_b32_e32 v95, 0xffff0000, v102
	v_lshlrev_b32_e32 v96, 16, v103
	v_and_b32_e32 v97, 0xffff0000, v103
	v_pk_add_f32 v[80:81], v[80:81], v[96:97]
	v_pk_add_f32 v[78:79], v[78:79], v[94:95]
	v_lshlrev_b32_e32 v96, 16, v105
	v_and_b32_e32 v97, 0xffff0000, v105
	v_lshlrev_b32_e32 v94, 16, v104
	v_and_b32_e32 v95, 0xffff0000, v104
	v_pk_add_f32 v[96:97], v[76:77], v[96:97]
	v_mul_f32_e32 v76, v78, v78
	v_mul_f32_e32 v77, v80, v80
	v_pk_add_f32 v[94:95], v[74:75], v[94:95]
	v_fmac_f32_e32 v76, v79, v79
	v_fmac_f32_e32 v77, v81, v81
	v_cvt_pk_bf16_f32 v74, v78, v79
	v_add_f32_e32 v76, v77, v76
	v_mul_f32_e32 v77, v94, v94
	v_mul_f32_e32 v78, v97, v97
	v_fmac_f32_e32 v77, v95, v95
	v_fmac_f32_e32 v78, v96, v96
	v_add_f32_e32 v77, v78, v77
	v_add_f32_e32 v102, v77, v76
	s_waitcnt vmcnt(4)
	v_lshlrev_b32_e32 v76, 16, v98
	v_and_b32_e32 v77, 0xffff0000, v98
	v_lshlrev_b32_e32 v78, 16, v99
	v_and_b32_e32 v79, 0xffff0000, v99
	v_pk_add_f32 v[72:73], v[72:73], v[78:79]
	v_pk_add_f32 v[70:71], v[70:71], v[76:77]
	v_lshlrev_b32_e32 v76, 16, v100
	v_and_b32_e32 v77, 0xffff0000, v100
	v_cvt_pk_bf16_f32 v75, v80, v81
	v_lshlrev_b32_e32 v78, 16, v101
	v_and_b32_e32 v79, 0xffff0000, v101
	v_pk_add_f32 v[80:81], v[66:67], v[76:77]
	v_mul_f32_e32 v66, v70, v70
	v_mul_f32_e32 v67, v72, v72
	v_pk_add_f32 v[78:79], v[68:69], v[78:79]
	v_fmac_f32_e32 v66, v71, v71
	v_fmac_f32_e32 v67, v73, v73
	v_add_f32_e32 v66, v67, v66
	v_mul_f32_e32 v67, v80, v80
	v_mul_f32_e32 v68, v79, v79
	v_fmac_f32_e32 v67, v81, v81
	v_fmac_f32_e32 v68, v78, v78
	v_add_f32_e32 v67, v68, v67
	v_add_f32_e32 v66, v67, v66
	v_add_f32_e32 v66, v102, v66
	v_cvt_pk_bf16_f32 v76, v94, v95
	v_cvt_pk_bf16_f32 v77, v96, v97
	global_store_dwordx4 v[108:109], v[74:77], off
	v_cvt_pk_bf16_f32 v68, v70, v71
	s_nop 0
	v_mov_b32_e32 v67, v66
	v_mov_b32_e32 v190, v66
	s_nop 1
	v_permlane16_swap_b32 v67, v190
	v_add_f32_e32 v66, v67, v190
	v_mov_b32_e32 v67, v66
	v_mov_b32_e32 v190, v66
	s_nop 1
	v_permlane32_swap_b32 v190, v67
	v_cvt_pk_bf16_f32 v69, v72, v73
	v_cvt_pk_bf16_f32 v70, v80, v81
	v_cvt_pk_bf16_f32 v71, v78, v79
	global_store_dwordx4 v[108:109], v[68:71], off offset:256
	s_and_saveexec_b64 s[20:21], s[0:1]
	s_cbranch_execz .LBB0_543
	v_lshlrev_b64 v[68:69], 7, v[106:107]
	v_lshl_add_u64 v[68:69], s[6:7], 0, v[68:69]
	v_lshl_add_u64 v[68:69], s[18:19], 2, v[68:69]
	s_lshl_b32 s40, s51, 2
	v_lshl_add_u64 v[68:69], v[68:69], 0, s[40:41]
	s_nop 0
	v_add_f32_e32 v66, v66, v67
	global_store_dword v[68:69], v66, off
.LBB0_543:
	s_or_b64 exec, exec, s[20:21]
	v_or_b32_e32 v66, 16, v90
	s_waitcnt lgkmcnt(0)
	v_ashrrev_i32_e32 v67, 31, v66
	v_lshlrev_b64 v[66:67], 11, v[66:67]
	v_lshl_add_u64 v[66:67], s[8:9], 0, v[66:67]
	v_lshl_add_u64 v[74:75], v[150:151], 1, v[66:67]
	global_load_dwordx4 v[70:73], v[74:75], off
	global_load_dwordx4 v[66:69], v[74:75], off offset:256
	s_waitcnt vmcnt(5)
	v_lshlrev_b32_e32 v76, 16, v86
	v_and_b32_e32 v77, 0xffff0000, v86
	v_lshlrev_b32_e32 v78, 16, v87
	v_and_b32_e32 v79, 0xffff0000, v87
	v_pk_add_f32 v[64:65], v[64:65], v[78:79]
	v_pk_add_f32 v[62:63], v[62:63], v[76:77]
	v_lshlrev_b32_e32 v78, 16, v89
	v_and_b32_e32 v79, 0xffff0000, v89
	v_lshlrev_b32_e32 v76, 16, v88
	v_and_b32_e32 v77, 0xffff0000, v88
	v_pk_add_f32 v[78:79], v[60:61], v[78:79]
	v_mul_f32_e32 v60, v62, v62
	v_mul_f32_e32 v61, v64, v64
	v_pk_add_f32 v[76:77], v[58:59], v[76:77]
	v_fmac_f32_e32 v60, v63, v63
	v_fmac_f32_e32 v61, v65, v65
	v_cvt_pk_bf16_f32 v58, v62, v63
	v_add_f32_e32 v60, v61, v60
	v_mul_f32_e32 v61, v76, v76
	v_mul_f32_e32 v62, v79, v79
	v_fmac_f32_e32 v61, v77, v77
	v_fmac_f32_e32 v62, v78, v78
	v_add_f32_e32 v61, v62, v61
	v_add_f32_e32 v80, v61, v60
	s_waitcnt vmcnt(4)
	v_lshlrev_b32_e32 v60, 16, v82
	v_and_b32_e32 v61, 0xffff0000, v82
	v_lshlrev_b32_e32 v62, 16, v83
	v_and_b32_e32 v63, 0xffff0000, v83
	v_pk_add_f32 v[56:57], v[56:57], v[62:63]
	v_pk_add_f32 v[54:55], v[54:55], v[60:61]
	v_lshlrev_b32_e32 v60, 16, v84
	v_and_b32_e32 v61, 0xffff0000, v84
	v_cvt_pk_bf16_f32 v59, v64, v65
	v_lshlrev_b32_e32 v62, 16, v85
	v_and_b32_e32 v63, 0xffff0000, v85
	v_pk_add_f32 v[64:65], v[50:51], v[60:61]
	v_mul_f32_e32 v50, v54, v54
	v_mul_f32_e32 v51, v56, v56
	v_pk_add_f32 v[62:63], v[52:53], v[62:63]
	v_fmac_f32_e32 v50, v55, v55
	v_fmac_f32_e32 v51, v57, v57
	v_add_f32_e32 v50, v51, v50
	v_mul_f32_e32 v51, v64, v64
	v_mul_f32_e32 v52, v63, v63
	v_fmac_f32_e32 v51, v65, v65
	v_fmac_f32_e32 v52, v62, v62
	v_add_f32_e32 v51, v52, v51
	v_add_f32_e32 v50, v51, v50
	v_add_f32_e32 v50, v80, v50
	v_cvt_pk_bf16_f32 v60, v76, v77
	v_cvt_pk_bf16_f32 v61, v78, v79
	global_store_dwordx4 v[92:93], v[58:61], off
	v_cvt_pk_bf16_f32 v52, v54, v55
	s_nop 0
	v_mov_b32_e32 v51, v50
	v_mov_b32_e32 v190, v50
	s_nop 1
	v_permlane16_swap_b32 v51, v190
	v_add_f32_e32 v50, v51, v190
	v_mov_b32_e32 v51, v50
	v_mov_b32_e32 v190, v50
	s_nop 1
	v_permlane32_swap_b32 v190, v51
	v_cvt_pk_bf16_f32 v53, v56, v57
	v_cvt_pk_bf16_f32 v54, v64, v65
	v_cvt_pk_bf16_f32 v55, v62, v63
	global_store_dwordx4 v[92:93], v[52:55], off offset:256
	s_and_saveexec_b64 s[20:21], s[0:1]
	s_cbranch_execz .LBB0_545
	v_lshlrev_b64 v[52:53], 7, v[90:91]
	v_lshl_add_u64 v[52:53], s[6:7], 0, v[52:53]
	v_lshl_add_u64 v[52:53], s[18:19], 2, v[52:53]
	s_lshl_b32 s40, s51, 2
	v_lshl_add_u64 v[52:53], v[52:53], 0, s[40:41]
	s_nop 0
	v_add_f32_e32 v50, v50, v51
	global_store_dword v[52:53], v50, off
.LBB0_545:
	s_or_b64 exec, exec, s[20:21]
	v_or_b32_e32 v50, 32, v90
	s_waitcnt lgkmcnt(0)
	v_ashrrev_i32_e32 v51, 31, v50
	v_lshlrev_b64 v[50:51], 11, v[50:51]
	v_lshl_add_u64 v[50:51], s[8:9], 0, v[50:51]
	v_lshl_add_u64 v[58:59], v[150:151], 1, v[50:51]
	global_load_dwordx4 v[54:57], v[58:59], off
	global_load_dwordx4 v[50:53], v[58:59], off offset:256
	s_waitcnt vmcnt(5)
	v_lshlrev_b32_e32 v60, 16, v70
	v_and_b32_e32 v61, 0xffff0000, v70
	v_lshlrev_b32_e32 v62, 16, v71
	v_and_b32_e32 v63, 0xffff0000, v71
	v_pk_add_f32 v[48:49], v[48:49], v[62:63]
	v_pk_add_f32 v[46:47], v[46:47], v[60:61]
	v_lshlrev_b32_e32 v62, 16, v73
	v_and_b32_e32 v63, 0xffff0000, v73
	v_lshlrev_b32_e32 v60, 16, v72
	v_and_b32_e32 v61, 0xffff0000, v72
	v_pk_add_f32 v[62:63], v[44:45], v[62:63]
	v_mul_f32_e32 v44, v46, v46
	v_mul_f32_e32 v45, v48, v48
	v_pk_add_f32 v[60:61], v[42:43], v[60:61]
	v_fmac_f32_e32 v44, v47, v47
	v_fmac_f32_e32 v45, v49, v49
	v_cvt_pk_bf16_f32 v42, v46, v47
	v_add_f32_e32 v44, v45, v44
	v_mul_f32_e32 v45, v60, v60
	v_mul_f32_e32 v46, v63, v63
	v_fmac_f32_e32 v45, v61, v61
	v_fmac_f32_e32 v46, v62, v62
	v_add_f32_e32 v45, v46, v45
	v_add_f32_e32 v64, v45, v44
	s_waitcnt vmcnt(4)
	v_lshlrev_b32_e32 v44, 16, v66
	v_and_b32_e32 v45, 0xffff0000, v66
	v_lshlrev_b32_e32 v46, 16, v67
	v_and_b32_e32 v47, 0xffff0000, v67
	v_pk_add_f32 v[40:41], v[40:41], v[46:47]
	v_pk_add_f32 v[38:39], v[38:39], v[44:45]
	v_lshlrev_b32_e32 v44, 16, v68
	v_and_b32_e32 v45, 0xffff0000, v68
	v_cvt_pk_bf16_f32 v43, v48, v49
	v_lshlrev_b32_e32 v46, 16, v69
	v_and_b32_e32 v47, 0xffff0000, v69
	v_pk_add_f32 v[48:49], v[34:35], v[44:45]
	v_mul_f32_e32 v34, v38, v38
	v_mul_f32_e32 v35, v40, v40
	v_pk_add_f32 v[46:47], v[36:37], v[46:47]
	v_fmac_f32_e32 v34, v39, v39
	v_fmac_f32_e32 v35, v41, v41
	v_add_f32_e32 v34, v35, v34
	v_mul_f32_e32 v35, v48, v48
	v_mul_f32_e32 v36, v47, v47
	v_fmac_f32_e32 v35, v49, v49
	v_fmac_f32_e32 v36, v46, v46
	v_add_f32_e32 v35, v36, v35
	v_add_f32_e32 v34, v35, v34
	v_add_f32_e32 v34, v64, v34
	v_cvt_pk_bf16_f32 v44, v60, v61
	v_cvt_pk_bf16_f32 v45, v62, v63
	global_store_dwordx4 v[74:75], v[42:45], off
	v_cvt_pk_bf16_f32 v36, v38, v39
	s_nop 0
	v_mov_b32_e32 v35, v34
	v_mov_b32_e32 v190, v34
	s_nop 1
	v_permlane16_swap_b32 v35, v190
	v_add_f32_e32 v34, v35, v190
	v_mov_b32_e32 v35, v34
	v_mov_b32_e32 v190, v34
	s_nop 1
	v_permlane32_swap_b32 v190, v35
	v_cvt_pk_bf16_f32 v37, v40, v41
	v_cvt_pk_bf16_f32 v38, v48, v49
	v_cvt_pk_bf16_f32 v39, v46, v47
	global_store_dwordx4 v[74:75], v[36:39], off offset:256
	s_and_saveexec_b64 s[20:21], s[0:1]
	s_cbranch_execz .LBB0_547
	v_add_u32_e32 v36, 0x90, v148
	v_ashrrev_i32_e32 v37, 31, v36
	v_lshlrev_b64 v[36:37], 7, v[36:37]
	v_lshl_add_u64 v[36:37], s[6:7], 0, v[36:37]
	v_lshl_add_u64 v[36:37], s[18:19], 2, v[36:37]
	s_lshl_b32 s40, s51, 2
	v_lshl_add_u64 v[36:37], v[36:37], 0, s[40:41]
	s_nop 0
	v_add_f32_e32 v34, v34, v35
	global_store_dword v[36:37], v34, off
.LBB0_547:
	s_or_b64 exec, exec, s[20:21]
	v_or_b32_e32 v34, 48, v90
	s_waitcnt lgkmcnt(0)
	v_ashrrev_i32_e32 v35, 31, v34
	v_lshlrev_b64 v[34:35], 11, v[34:35]
	v_lshl_add_u64 v[34:35], s[8:9], 0, v[34:35]
	v_lshl_add_u64 v[42:43], v[150:151], 1, v[34:35]
	global_load_dwordx4 v[38:41], v[42:43], off
	global_load_dwordx4 v[34:37], v[42:43], off offset:256
	s_waitcnt vmcnt(5)
	v_lshlrev_b32_e32 v44, 16, v54
	v_and_b32_e32 v45, 0xffff0000, v54
	v_lshlrev_b32_e32 v46, 16, v55
	v_and_b32_e32 v47, 0xffff0000, v55
	v_pk_add_f32 v[32:33], v[32:33], v[46:47]
	v_pk_add_f32 v[30:31], v[30:31], v[44:45]
	v_lshlrev_b32_e32 v46, 16, v57
	v_and_b32_e32 v47, 0xffff0000, v57
	v_lshlrev_b32_e32 v44, 16, v56
	v_and_b32_e32 v45, 0xffff0000, v56
	v_pk_add_f32 v[46:47], v[28:29], v[46:47]
	v_mul_f32_e32 v28, v30, v30
	v_mul_f32_e32 v29, v32, v32
	v_pk_add_f32 v[44:45], v[26:27], v[44:45]
	v_fmac_f32_e32 v28, v31, v31
	v_fmac_f32_e32 v29, v33, v33
	v_cvt_pk_bf16_f32 v26, v30, v31
	v_add_f32_e32 v28, v29, v28
	v_mul_f32_e32 v29, v44, v44
	v_mul_f32_e32 v30, v47, v47
	v_fmac_f32_e32 v29, v45, v45
	v_fmac_f32_e32 v30, v46, v46
	v_add_f32_e32 v29, v30, v29
	v_add_f32_e32 v48, v29, v28
	s_waitcnt vmcnt(4)
	v_lshlrev_b32_e32 v28, 16, v50
	v_and_b32_e32 v29, 0xffff0000, v50
	v_lshlrev_b32_e32 v30, 16, v51
	v_and_b32_e32 v31, 0xffff0000, v51
	v_pk_add_f32 v[24:25], v[24:25], v[30:31]
	v_pk_add_f32 v[22:23], v[22:23], v[28:29]
	v_lshlrev_b32_e32 v28, 16, v52
	v_and_b32_e32 v29, 0xffff0000, v52
	v_cvt_pk_bf16_f32 v27, v32, v33
	v_lshlrev_b32_e32 v30, 16, v53
	v_and_b32_e32 v31, 0xffff0000, v53
	v_pk_add_f32 v[32:33], v[18:19], v[28:29]
	v_mul_f32_e32 v18, v22, v22
	v_mul_f32_e32 v19, v24, v24
	v_pk_add_f32 v[30:31], v[20:21], v[30:31]
	v_fmac_f32_e32 v18, v23, v23
	v_fmac_f32_e32 v19, v25, v25
	v_add_f32_e32 v18, v19, v18
	v_mul_f32_e32 v19, v32, v32
	v_mul_f32_e32 v20, v31, v31
	v_fmac_f32_e32 v19, v33, v33
	v_fmac_f32_e32 v20, v30, v30
	v_add_f32_e32 v19, v20, v19
	v_add_f32_e32 v18, v19, v18
	v_add_f32_e32 v18, v48, v18
	v_cvt_pk_bf16_f32 v28, v44, v45
	v_cvt_pk_bf16_f32 v29, v46, v47
	global_store_dwordx4 v[58:59], v[26:29], off
	v_cvt_pk_bf16_f32 v20, v22, v23
	s_nop 0
	v_mov_b32_e32 v19, v18
	v_mov_b32_e32 v190, v18
	s_nop 1
	v_permlane16_swap_b32 v19, v190
	v_add_f32_e32 v18, v19, v190
	v_mov_b32_e32 v19, v18
	v_mov_b32_e32 v190, v18
	s_nop 1
	v_permlane32_swap_b32 v190, v19
	v_cvt_pk_bf16_f32 v21, v24, v25
	v_cvt_pk_bf16_f32 v22, v32, v33
	v_cvt_pk_bf16_f32 v23, v30, v31
	global_store_dwordx4 v[58:59], v[20:23], off offset:256
	s_and_saveexec_b64 s[20:21], s[0:1]
	s_cbranch_execz .LBB0_549
	v_add_u32_e32 v20, 0xa0, v148
	v_ashrrev_i32_e32 v21, 31, v20
	v_lshlrev_b64 v[20:21], 7, v[20:21]
	v_lshl_add_u64 v[20:21], s[6:7], 0, v[20:21]
	v_lshl_add_u64 v[20:21], s[18:19], 2, v[20:21]
	s_lshl_b32 s40, s51, 2
	v_lshl_add_u64 v[20:21], v[20:21], 0, s[40:41]
	s_nop 0
	v_add_f32_e32 v18, v18, v19
	global_store_dword v[20:21], v18, off
.LBB0_549:
	s_or_b64 exec, exec, s[20:21]
	s_waitcnt vmcnt(3)
	v_lshlrev_b32_e32 v18, 16, v38
	s_waitcnt lgkmcnt(0)
	v_and_b32_e32 v19, 0xffff0000, v38
	v_lshlrev_b32_e32 v20, 16, v39
	v_and_b32_e32 v21, 0xffff0000, v39
	v_pk_add_f32 v[16:17], v[16:17], v[20:21]
	v_pk_add_f32 v[14:15], v[14:15], v[18:19]
	v_lshlrev_b32_e32 v20, 16, v41
	v_and_b32_e32 v21, 0xffff0000, v41
	v_lshlrev_b32_e32 v18, 16, v40
	v_and_b32_e32 v19, 0xffff0000, v40
	v_pk_add_f32 v[20:21], v[12:13], v[20:21]
	v_mul_f32_e32 v12, v14, v14
	v_mul_f32_e32 v13, v16, v16
	v_pk_add_f32 v[18:19], v[10:11], v[18:19]
	v_fmac_f32_e32 v12, v15, v15
	v_fmac_f32_e32 v13, v17, v17
	v_cvt_pk_bf16_f32 v10, v14, v15
	v_add_f32_e32 v12, v13, v12
	v_mul_f32_e32 v13, v18, v18
	v_mul_f32_e32 v14, v21, v21
	v_fmac_f32_e32 v13, v19, v19
	v_fmac_f32_e32 v14, v20, v20
	v_add_f32_e32 v13, v14, v13
	v_add_f32_e32 v22, v13, v12
	s_waitcnt vmcnt(2)
	v_lshlrev_b32_e32 v12, 16, v34
	v_and_b32_e32 v13, 0xffff0000, v34
	v_lshlrev_b32_e32 v14, 16, v35
	v_and_b32_e32 v15, 0xffff0000, v35
	v_pk_add_f32 v[8:9], v[8:9], v[14:15]
	v_pk_add_f32 v[6:7], v[6:7], v[12:13]
	v_lshlrev_b32_e32 v12, 16, v36
	v_and_b32_e32 v13, 0xffff0000, v36
	v_cvt_pk_bf16_f32 v11, v16, v17
	v_lshlrev_b32_e32 v14, 16, v37
	v_and_b32_e32 v15, 0xffff0000, v37
	v_pk_add_f32 v[16:17], v[2:3], v[12:13]
	v_mul_f32_e32 v2, v6, v6
	v_mul_f32_e32 v3, v8, v8
	v_pk_add_f32 v[14:15], v[4:5], v[14:15]
	v_fmac_f32_e32 v2, v7, v7
	v_fmac_f32_e32 v3, v9, v9
	v_add_f32_e32 v2, v3, v2
	v_mul_f32_e32 v3, v16, v16
	v_mul_f32_e32 v4, v15, v15
	v_fmac_f32_e32 v3, v17, v17
	v_fmac_f32_e32 v4, v14, v14
	v_add_f32_e32 v3, v4, v3
	v_add_f32_e32 v2, v3, v2
	v_add_f32_e32 v2, v22, v2
	v_cvt_pk_bf16_f32 v12, v18, v19
	v_cvt_pk_bf16_f32 v13, v20, v21
	global_store_dwordx4 v[42:43], v[10:13], off
	v_cvt_pk_bf16_f32 v4, v6, v7
	s_nop 0
	v_mov_b32_e32 v3, v2
	v_mov_b32_e32 v190, v2
	s_nop 1
	v_permlane16_swap_b32 v3, v190
	v_add_f32_e32 v2, v3, v190
	v_mov_b32_e32 v3, v2
	v_mov_b32_e32 v190, v2
	s_nop 1
	v_permlane32_swap_b32 v190, v3
	v_cvt_pk_bf16_f32 v5, v8, v9
	v_cvt_pk_bf16_f32 v6, v16, v17
	v_cvt_pk_bf16_f32 v7, v14, v15
	global_store_dwordx4 v[42:43], v[4:7], off offset:256
	s_and_saveexec_b64 s[20:21], s[0:1]
	s_cbranch_execz .LBB0_526
	v_add_u32_e32 v4, 0xb0, v148
	v_ashrrev_i32_e32 v5, 31, v4
	v_lshlrev_b64 v[4:5], 7, v[4:5]
	v_lshl_add_u64 v[4:5], s[6:7], 0, v[4:5]
	v_lshl_add_u64 v[4:5], s[18:19], 2, v[4:5]
	s_lshl_b32 s40, s51, 2
	v_lshl_add_u64 v[4:5], v[4:5], 0, s[40:41]
	s_nop 0
	v_add_f32_e32 v2, v2, v3
	global_store_dword v[4:5], v2, off
	s_branch .LBB0_526

.LBB0_939:
	s_add_u32 s24, s22, 0xfffc0080
	s_addc_u32 s25, s23, -1
	s_add_i32 s52, 0, 0x10000
	s_cmp_eq_u32 s51, 12
	s_cselect_b32 s27, s13, s25
	s_cselect_b32 s26, s19, s24
	s_cselect_b32 s25, s11, s50
	s_cselect_b32 s24, s21, s49
	s_add_i32 s54, 0, 0x14000
	v_add_u32_e32 v142, s52, v167
	v_add_u32_e32 v164, s54, v167
	ds_read_b128 v[130:133], v142
	ds_read_b128 v[134:137], v142 offset:1024
	ds_read_b128 v[138:141], v142 offset:2048
	ds_read_b128 v[142:145], v142 offset:3072
	ds_read_b128 v[156:159], v164
	ds_read_b128 v[160:163], v164 offset:1024
	ds_read_b128 v[170:173], v164 offset:2048
	ds_read_b128 v[174:177], v164 offset:3072
	v_lshl_add_u64 v[164:165], s[22:23], 0, v[152:153]
	s_add_i32 m0, s38, 0xc000
	ds_read_b128 v[178:181], v169
	ds_read_b128 v[182:185], v169 offset:1024
	ds_read_b128 v[186:189], v169 offset:2048
	ds_read_b128 v[190:193], v169 offset:3072
	ds_read_b128 v[202:205], v169 offset:4096
	ds_read_b128 v[206:209], v169 offset:5120
	ds_read_b128 v[210:213], v169 offset:6144
	ds_read_b128 v[214:217], v169 offset:7168
	global_load_lds_dwordx4 v[164:165], off
	v_lshl_add_u64 v[164:165], s[22:23], 0, v[154:155]
	s_add_i32 m0, s38, 0xe000
	s_nop 0
	global_load_lds_dwordx4 v[164:165], off
	s_waitcnt vmcnt(8)
	s_waitcnt lgkmcnt(0)
	s_barrier
	s_waitcnt lgkmcnt(0)
	v_mfma_f32_16x16x32_bf16 v[126:129], v[130:133], v[178:181], v[126:129]
	v_mfma_f32_16x16x32_bf16 v[122:125], v[138:141], v[178:181], v[122:125]
	v_mfma_f32_16x16x32_bf16 v[110:113], v[130:133], v[186:189], v[110:113]
	v_mfma_f32_16x16x32_bf16 v[106:109], v[138:141], v[186:189], v[106:109]
	v_mfma_f32_16x16x32_bf16 v[94:97], v[130:133], v[202:205], v[94:97]
	v_mfma_f32_16x16x32_bf16 v[90:93], v[138:141], v[202:205], v[90:93]
	v_mfma_f32_16x16x32_bf16 v[78:81], v[130:133], v[210:213], v[78:81]
	v_mfma_f32_16x16x32_bf16 v[74:77], v[138:141], v[210:213], v[74:77]
	v_mfma_f32_16x16x32_bf16 v[126:129], v[134:137], v[182:185], v[126:129]
	v_mfma_f32_16x16x32_bf16 v[122:125], v[142:145], v[182:185], v[122:125]
	v_mfma_f32_16x16x32_bf16 v[110:113], v[134:137], v[190:193], v[110:113]
	v_mfma_f32_16x16x32_bf16 v[106:109], v[142:145], v[190:193], v[106:109]
	v_mfma_f32_16x16x32_bf16 v[94:97], v[134:137], v[206:209], v[94:97]
	v_mfma_f32_16x16x32_bf16 v[90:93], v[142:145], v[206:209], v[90:93]
	v_mfma_f32_16x16x32_bf16 v[78:81], v[134:137], v[214:217], v[78:81]
	v_mfma_f32_16x16x32_bf16 v[74:77], v[142:145], v[214:217], v[74:77]
	v_mfma_f32_16x16x32_bf16 v[118:121], v[156:159], v[178:181], v[118:121]
	v_mfma_f32_16x16x32_bf16 v[114:117], v[170:173], v[178:181], v[114:117]
	v_mfma_f32_16x16x32_bf16 v[102:105], v[156:159], v[186:189], v[102:105]
	v_mfma_f32_16x16x32_bf16 v[98:101], v[170:173], v[186:189], v[98:101]
	v_mfma_f32_16x16x32_bf16 v[86:89], v[156:159], v[202:205], v[86:89]
	v_mfma_f32_16x16x32_bf16 v[82:85], v[170:173], v[202:205], v[82:85]
	v_mfma_f32_16x16x32_bf16 v[70:73], v[156:159], v[210:213], v[70:73]
	v_mfma_f32_16x16x32_bf16 v[66:69], v[170:173], v[210:213], v[66:69]
	v_mfma_f32_16x16x32_bf16 v[118:121], v[160:163], v[182:185], v[118:121]
	v_mfma_f32_16x16x32_bf16 v[114:117], v[174:177], v[182:185], v[114:117]
	v_mfma_f32_16x16x32_bf16 v[102:105], v[160:163], v[190:193], v[102:105]
	v_mfma_f32_16x16x32_bf16 v[98:101], v[174:177], v[190:193], v[98:101]
	v_mfma_f32_16x16x32_bf16 v[86:89], v[160:163], v[206:209], v[86:89]
	v_mfma_f32_16x16x32_bf16 v[82:85], v[174:177], v[206:209], v[82:85]
	v_mfma_f32_16x16x32_bf16 v[70:73], v[160:163], v[214:217], v[70:73]
	v_mfma_f32_16x16x32_bf16 v[66:69], v[174:177], v[214:217], v[66:69]
	s_barrier
	s_add_i32 s52, s52, s37
	v_lshl_add_u64 v[164:165], s[24:25], 0, v[194:195]
	s_mov_b32 m0, s52
	ds_read_b128 v[178:181], v169 offset:16384
	ds_read_b128 v[182:185], v169 offset:17408
	ds_read_b128 v[186:189], v169 offset:18432
	ds_read_b128 v[190:193], v169 offset:19456
	ds_read_b128 v[202:205], v169 offset:20480
	ds_read_b128 v[206:209], v169 offset:21504
	ds_read_b128 v[210:213], v169 offset:22528
	ds_read_b128 v[214:217], v169 offset:23552
	global_load_lds_dwordx4 v[164:165], off
	s_add_i32 m0, s52, 0x2000
	s_add_u32 s52, s24, 0x40000
	v_lshl_add_u64 v[218:219], s[24:25], 0, v[150:151]
	s_addc_u32 s53, s25, 0
	s_add_i32 s54, s54, s37
	global_load_lds_dwordx4 v[218:219], off
	v_lshl_add_u64 v[220:221], s[52:53], 0, v[194:195]
	s_mov_b32 m0, s54
	v_lshl_add_u64 v[222:223], s[26:27], 0, v[148:149]
	global_load_lds_dwordx4 v[220:221], off
	v_lshl_add_u64 v[220:221], s[52:53], 0, v[150:151]
	s_add_i32 m0, s54, 0x2000
	s_nop 0
	global_load_lds_dwordx4 v[220:221], off
	v_lshl_add_u64 v[220:221], s[26:27], 0, v[146:147]
	s_mov_b32 m0, s38
	s_nop 0
	global_load_lds_dwordx4 v[220:221], off
	s_mov_b32 m0, s39
	s_nop 0
	global_load_lds_dwordx4 v[222:223], off
	s_waitcnt vmcnt(8)
	s_waitcnt lgkmcnt(0)
	s_barrier
	s_waitcnt lgkmcnt(0)
	v_mfma_f32_16x16x32_bf16 v[62:65], v[130:133], v[178:181], v[62:65]
	v_mfma_f32_16x16x32_bf16 v[58:61], v[138:141], v[178:181], v[58:61]
	v_mfma_f32_16x16x32_bf16 v[46:49], v[130:133], v[186:189], v[46:49]
	v_mfma_f32_16x16x32_bf16 v[42:45], v[138:141], v[186:189], v[42:45]
	v_mfma_f32_16x16x32_bf16 v[30:33], v[130:133], v[202:205], v[30:33]
	v_mfma_f32_16x16x32_bf16 v[26:29], v[138:141], v[202:205], v[26:29]
	v_mfma_f32_16x16x32_bf16 v[14:17], v[130:133], v[210:213], v[14:17]
	v_mfma_f32_16x16x32_bf16 v[10:13], v[138:141], v[210:213], v[10:13]
	v_mfma_f32_16x16x32_bf16 v[62:65], v[134:137], v[182:185], v[62:65]
	v_mfma_f32_16x16x32_bf16 v[58:61], v[142:145], v[182:185], v[58:61]
	v_mfma_f32_16x16x32_bf16 v[46:49], v[134:137], v[190:193], v[46:49]
	v_mfma_f32_16x16x32_bf16 v[42:45], v[142:145], v[190:193], v[42:45]
	v_mfma_f32_16x16x32_bf16 v[30:33], v[134:137], v[206:209], v[30:33]
	v_mfma_f32_16x16x32_bf16 v[26:29], v[142:145], v[206:209], v[26:29]
	v_mfma_f32_16x16x32_bf16 v[14:17], v[134:137], v[214:217], v[14:17]
	v_mfma_f32_16x16x32_bf16 v[10:13], v[142:145], v[214:217], v[10:13]
	v_mfma_f32_16x16x32_bf16 v[54:57], v[156:159], v[178:181], v[54:57]
	v_mfma_f32_16x16x32_bf16 v[50:53], v[170:173], v[178:181], v[50:53]
	v_mfma_f32_16x16x32_bf16 v[38:41], v[156:159], v[186:189], v[38:41]
	v_mfma_f32_16x16x32_bf16 v[34:37], v[170:173], v[186:189], v[34:37]
	v_mfma_f32_16x16x32_bf16 v[22:25], v[156:159], v[202:205], v[22:25]
	v_mfma_f32_16x16x32_bf16 v[18:21], v[170:173], v[202:205], v[18:21]
	v_mfma_f32_16x16x32_bf16 v[6:9], v[156:159], v[210:213], v[6:9]
	v_mfma_f32_16x16x32_bf16 v[2:5], v[170:173], v[210:213], v[2:5]
	v_mfma_f32_16x16x32_bf16 v[54:57], v[160:163], v[182:185], v[54:57]
	v_mfma_f32_16x16x32_bf16 v[50:53], v[174:177], v[182:185], v[50:53]
	v_mfma_f32_16x16x32_bf16 v[38:41], v[160:163], v[190:193], v[38:41]
	v_mfma_f32_16x16x32_bf16 v[34:37], v[174:177], v[190:193], v[34:37]
	v_mfma_f32_16x16x32_bf16 v[22:25], v[160:163], v[206:209], v[22:25]
	v_mfma_f32_16x16x32_bf16 v[18:21], v[174:177], v[206:209], v[18:21]
	v_mfma_f32_16x16x32_bf16 v[6:9], v[160:163], v[214:217], v[6:9]
	v_mfma_f32_16x16x32_bf16 v[2:5], v[174:177], v[214:217], v[2:5]
	s_barrier
	s_add_i32 s52, 0, 0x18000
	s_add_i32 s53, 0, 0x1c000
	v_add_u32_e32 v142, s52, v167
	v_add_u32_e32 v174, s53, v167
	ds_read_b128 v[130:133], v142
	ds_read_b128 v[134:137], v142 offset:1024
	ds_read_b128 v[138:141], v142 offset:2048
	ds_read_b128 v[142:145], v142 offset:3072
	ds_read_b128 v[156:159], v174
	ds_read_b128 v[160:163], v174 offset:1024
	ds_read_b128 v[170:173], v174 offset:2048
	ds_read_b128 v[174:177], v174 offset:3072
	s_add_u32 s26, s26, 0x40000
	s_addc_u32 s27, s27, 0
	s_mov_b32 m0, s42
	v_lshl_add_u64 v[224:225], s[26:27], 0, v[146:147]
	ds_read_b128 v[178:181], v169 offset:32768
	ds_read_b128 v[182:185], v169 offset:33792
	ds_read_b128 v[186:189], v169 offset:34816
	ds_read_b128 v[190:193], v169 offset:35840
	ds_read_b128 v[202:205], v169 offset:36864
	ds_read_b128 v[206:209], v169 offset:37888
	ds_read_b128 v[210:213], v169 offset:38912
	ds_read_b128 v[214:217], v169 offset:39936
	global_load_lds_dwordx4 v[224:225], off
	v_lshl_add_u64 v[224:225], s[26:27], 0, v[148:149]
	s_mov_b32 m0, s43
	s_nop 0
	global_load_lds_dwordx4 v[224:225], off
	s_waitcnt vmcnt(8)
	s_waitcnt lgkmcnt(0)
	s_barrier
	s_waitcnt lgkmcnt(0)
	v_mfma_f32_16x16x32_bf16 v[126:129], v[130:133], v[178:181], v[126:129]
	v_mfma_f32_16x16x32_bf16 v[122:125], v[138:141], v[178:181], v[122:125]
	v_mfma_f32_16x16x32_bf16 v[110:113], v[130:133], v[186:189], v[110:113]
	v_mfma_f32_16x16x32_bf16 v[106:109], v[138:141], v[186:189], v[106:109]
	v_mfma_f32_16x16x32_bf16 v[94:97], v[130:133], v[202:205], v[94:97]
	v_mfma_f32_16x16x32_bf16 v[90:93], v[138:141], v[202:205], v[90:93]
	v_mfma_f32_16x16x32_bf16 v[78:81], v[130:133], v[210:213], v[78:81]
	v_mfma_f32_16x16x32_bf16 v[74:77], v[138:141], v[210:213], v[74:77]
	v_mfma_f32_16x16x32_bf16 v[126:129], v[134:137], v[182:185], v[126:129]
	v_mfma_f32_16x16x32_bf16 v[122:125], v[142:145], v[182:185], v[122:125]
	v_mfma_f32_16x16x32_bf16 v[110:113], v[134:137], v[190:193], v[110:113]
	v_mfma_f32_16x16x32_bf16 v[106:109], v[142:145], v[190:193], v[106:109]
	v_mfma_f32_16x16x32_bf16 v[94:97], v[134:137], v[206:209], v[94:97]
	v_mfma_f32_16x16x32_bf16 v[90:93], v[142:145], v[206:209], v[90:93]
	v_mfma_f32_16x16x32_bf16 v[78:81], v[134:137], v[214:217], v[78:81]
	v_mfma_f32_16x16x32_bf16 v[74:77], v[142:145], v[214:217], v[74:77]
	v_mfma_f32_16x16x32_bf16 v[118:121], v[156:159], v[178:181], v[118:121]
	v_mfma_f32_16x16x32_bf16 v[114:117], v[170:173], v[178:181], v[114:117]
	v_mfma_f32_16x16x32_bf16 v[102:105], v[156:159], v[186:189], v[102:105]
	v_mfma_f32_16x16x32_bf16 v[98:101], v[170:173], v[186:189], v[98:101]
	v_mfma_f32_16x16x32_bf16 v[86:89], v[156:159], v[202:205], v[86:89]
	v_mfma_f32_16x16x32_bf16 v[82:85], v[170:173], v[202:205], v[82:85]
	v_mfma_f32_16x16x32_bf16 v[70:73], v[156:159], v[210:213], v[70:73]
	v_mfma_f32_16x16x32_bf16 v[66:69], v[170:173], v[210:213], v[66:69]
	v_mfma_f32_16x16x32_bf16 v[118:121], v[160:163], v[182:185], v[118:121]
	v_mfma_f32_16x16x32_bf16 v[114:117], v[174:177], v[182:185], v[114:117]
	v_mfma_f32_16x16x32_bf16 v[102:105], v[160:163], v[190:193], v[102:105]
	v_mfma_f32_16x16x32_bf16 v[98:101], v[174:177], v[190:193], v[98:101]
	v_mfma_f32_16x16x32_bf16 v[86:89], v[160:163], v[206:209], v[86:89]
	v_mfma_f32_16x16x32_bf16 v[82:85], v[174:177], v[206:209], v[82:85]
	v_mfma_f32_16x16x32_bf16 v[70:73], v[160:163], v[214:217], v[70:73]
	v_mfma_f32_16x16x32_bf16 v[66:69], v[174:177], v[214:217], v[66:69]
	s_barrier
	s_add_i32 s26, s52, s37
	v_lshl_add_u64 v[164:165], v[164:165], 0, s[92:93]
	s_mov_b32 m0, s26
	ds_read_b128 v[178:181], v169 offset:49152
	ds_read_b128 v[182:185], v169 offset:50176
	ds_read_b128 v[186:189], v169 offset:51200
	ds_read_b128 v[190:193], v169 offset:52224
	ds_read_b128 v[202:205], v169 offset:53248
	ds_read_b128 v[206:209], v169 offset:54272
	ds_read_b128 v[210:213], v169 offset:55296
	ds_read_b128 v[214:217], v169 offset:56320
	global_load_lds_dwordx4 v[164:165], off
	s_add_i32 m0, s26, 0x2000
	s_add_u32 s24, s24, 0x40080
	v_lshl_add_u64 v[164:165], v[218:219], 0, s[92:93]
	s_addc_u32 s25, s25, 0
	s_add_i32 s26, s53, s37
	global_load_lds_dwordx4 v[164:165], off
	v_lshl_add_u64 v[164:165], s[24:25], 0, v[194:195]
	s_mov_b32 m0, s26
	s_nop 0
	global_load_lds_dwordx4 v[164:165], off
	v_lshl_add_u64 v[164:165], s[24:25], 0, v[150:151]
	s_add_i32 m0, s26, 0x2000
	s_nop 0
	global_load_lds_dwordx4 v[164:165], off
	v_lshl_add_u64 v[164:165], v[220:221], 0, s[92:93]
	s_mov_b32 m0, s45
	s_nop 0
	global_load_lds_dwordx4 v[164:165], off
	v_lshl_add_u64 v[164:165], v[222:223], 0, s[92:93]
	s_mov_b32 m0, s46
	s_nop 0
	global_load_lds_dwordx4 v[164:165], off
	s_waitcnt vmcnt(8)
	s_waitcnt lgkmcnt(0)
	s_barrier
	s_waitcnt lgkmcnt(0)
	v_mfma_f32_16x16x32_bf16 v[62:65], v[130:133], v[178:181], v[62:65]
	v_mfma_f32_16x16x32_bf16 v[58:61], v[138:141], v[178:181], v[58:61]
	v_mfma_f32_16x16x32_bf16 v[46:49], v[130:133], v[186:189], v[46:49]
	v_mfma_f32_16x16x32_bf16 v[42:45], v[138:141], v[186:189], v[42:45]
	v_mfma_f32_16x16x32_bf16 v[30:33], v[130:133], v[202:205], v[30:33]
	v_mfma_f32_16x16x32_bf16 v[26:29], v[138:141], v[202:205], v[26:29]
	v_mfma_f32_16x16x32_bf16 v[14:17], v[130:133], v[210:213], v[14:17]
	v_mfma_f32_16x16x32_bf16 v[10:13], v[138:141], v[210:213], v[10:13]
	v_mfma_f32_16x16x32_bf16 v[62:65], v[134:137], v[182:185], v[62:65]
	v_mfma_f32_16x16x32_bf16 v[58:61], v[142:145], v[182:185], v[58:61]
	v_mfma_f32_16x16x32_bf16 v[46:49], v[134:137], v[190:193], v[46:49]
	v_mfma_f32_16x16x32_bf16 v[42:45], v[142:145], v[190:193], v[42:45]
	v_mfma_f32_16x16x32_bf16 v[30:33], v[134:137], v[206:209], v[30:33]
	v_mfma_f32_16x16x32_bf16 v[26:29], v[142:145], v[206:209], v[26:29]
	v_mfma_f32_16x16x32_bf16 v[14:17], v[134:137], v[214:217], v[14:17]
	v_mfma_f32_16x16x32_bf16 v[10:13], v[142:145], v[214:217], v[10:13]
	v_mfma_f32_16x16x32_bf16 v[54:57], v[156:159], v[178:181], v[54:57]
	v_mfma_f32_16x16x32_bf16 v[50:53], v[170:173], v[178:181], v[50:53]
	v_mfma_f32_16x16x32_bf16 v[38:41], v[156:159], v[186:189], v[38:41]
	v_mfma_f32_16x16x32_bf16 v[34:37], v[170:173], v[186:189], v[34:37]
	v_mfma_f32_16x16x32_bf16 v[22:25], v[156:159], v[202:205], v[22:25]
	v_mfma_f32_16x16x32_bf16 v[18:21], v[170:173], v[202:205], v[18:21]
	v_mfma_f32_16x16x32_bf16 v[6:9], v[156:159], v[210:213], v[6:9]
	v_mfma_f32_16x16x32_bf16 v[2:5], v[170:173], v[210:213], v[2:5]
	v_mfma_f32_16x16x32_bf16 v[54:57], v[160:163], v[182:185], v[54:57]
	v_mfma_f32_16x16x32_bf16 v[50:53], v[174:177], v[182:185], v[50:53]
	v_mfma_f32_16x16x32_bf16 v[38:41], v[160:163], v[190:193], v[38:41]
	v_mfma_f32_16x16x32_bf16 v[34:37], v[174:177], v[190:193], v[34:37]
	v_mfma_f32_16x16x32_bf16 v[22:25], v[160:163], v[206:209], v[22:25]
	v_mfma_f32_16x16x32_bf16 v[18:21], v[174:177], v[206:209], v[18:21]
	v_mfma_f32_16x16x32_bf16 v[6:9], v[160:163], v[214:217], v[6:9]
	v_mfma_f32_16x16x32_bf16 v[2:5], v[174:177], v[214:217], v[2:5]
	s_barrier
	s_add_i32 s51, s51, 2
	s_add_u32 s22, s22, 0x100
	s_addc_u32 s23, s23, 0
	s_add_u32 s49, s49, 0x100
	s_addc_u32 s50, s50, 0
	s_cmp_gt_u32 s51, 13
	s_cbranch_scc0 .LBB0_939
	v_lshl_add_u32 v156, s20, 8, v166
	v_lshl_or_b32 v158, s18, 8, v168
	v_ashrrev_i32_e32 v157, 31, v156
	v_lshlrev_b64 v[130:131], 11, v[156:157]
	v_ashrrev_i32_e32 v159, 31, v158
	v_lshl_add_u64 v[130:131], s[8:9], 0, v[130:131]
	v_lshlrev_b64 v[132:133], 1, v[158:159]
	v_lshl_add_u64 v[164:165], v[130:131], 0, v[132:133]
	global_load_dwordx4 v[142:145], v[164:165], off
	global_load_dwordx4 v[138:141], v[164:165], off offset:256
	v_or_b32_e32 v160, 16, v156
	v_ashrrev_i32_e32 v161, 31, v160
	v_lshlrev_b64 v[130:131], 11, v[160:161]
	v_lshl_add_u64 v[130:131], s[8:9], 0, v[130:131]
	v_lshl_add_u64 v[162:163], v[130:131], 0, v[132:133]
	global_load_dwordx4 v[134:137], v[162:163], off
	global_load_dwordx4 v[130:133], v[162:163], off offset:256
	v_and_b32_e32 v171, 64, v1
	v_xor_b32_e32 v170, 16, v1
	v_add_u32_e32 v171, 64, v171
	v_xor_b32_e32 v172, 32, v1
	v_cmp_lt_i32_e32 vcc, v170, v171
	s_lshl_b32 s18, s18, 2
	s_ashr_i32 s19, s18, 31
	v_cndmask_b32_e32 v170, v1, v170, vcc
	v_cmp_lt_i32_e32 vcc, v172, v171
	v_lshlrev_b32_e32 v170, 2, v170
	s_waitcnt vmcnt(0)
	v_and_b32_e32 v173, 0xffff0000, v142
	v_cndmask_b32_e32 v171, v1, v172, vcc
	v_lshlrev_b32_e32 v172, 16, v142
	v_lshlrev_b32_e32 v142, 16, v143
	v_and_b32_e32 v143, 0xffff0000, v143
	v_lshlrev_b32_e32 v174, 16, v144
	v_and_b32_e32 v175, 0xffff0000, v144
	v_lshlrev_b32_e32 v144, 16, v145
	v_and_b32_e32 v145, 0xffff0000, v145
	v_lshlrev_b32_e32 v176, 16, v138
	v_and_b32_e32 v177, 0xffff0000, v138
	v_lshlrev_b32_e32 v138, 16, v139
	v_and_b32_e32 v139, 0xffff0000, v139
	v_lshlrev_b32_e32 v178, 16, v140
	v_and_b32_e32 v179, 0xffff0000, v140
	v_lshlrev_b32_e32 v140, 16, v141
	v_and_b32_e32 v141, 0xffff0000, v141
	v_pk_add_f32 v[128:129], v[128:129], v[142:143]
	v_pk_add_f32 v[126:127], v[126:127], v[172:173]
	v_pk_add_f32 v[122:123], v[122:123], v[174:175]
	v_pk_add_f32 v[124:125], v[124:125], v[144:145]
	v_pk_add_f32 v[120:121], v[120:121], v[138:139]
	v_pk_add_f32 v[118:119], v[118:119], v[176:177]
	v_pk_add_f32 v[138:139], v[114:115], v[178:179]
	v_pk_add_f32 v[140:141], v[116:117], v[140:141]
	v_cvt_pk_bf16_f32 v114, v126, v127
	v_cvt_pk_bf16_f32 v115, v128, v129
	v_mul_f32_e32 v116, v126, v126
	v_mul_f32_e32 v117, v128, v128
	v_mul_f32_e32 v126, v122, v122
	v_mul_f32_e32 v128, v125, v125
	v_mul_f32_e32 v142, v118, v118
	v_mul_f32_e32 v143, v120, v120
	v_mul_f32_e32 v144, v138, v138
	v_mul_f32_e32 v145, v141, v141
	v_fmac_f32_e32 v116, v127, v127
	v_fmac_f32_e32 v117, v129, v129
	v_fmac_f32_e32 v126, v123, v123
	v_fmac_f32_e32 v128, v124, v124
	v_fmac_f32_e32 v142, v119, v119
	v_fmac_f32_e32 v143, v121, v121
	v_fmac_f32_e32 v144, v139, v139
	v_fmac_f32_e32 v145, v140, v140
	v_add_f32_e32 v116, v117, v116
	v_add_f32_e32 v117, v128, v126
	v_add_f32_e32 v126, v143, v142
	v_add_f32_e32 v127, v145, v144
	v_add_f32_e32 v116, v117, v116
	v_add_f32_e32 v117, v127, v126
	v_add_f32_e32 v126, v116, v117
	v_cvt_pk_bf16_f32 v116, v122, v123
	v_cvt_pk_bf16_f32 v117, v124, v125
	global_store_dwordx4 v[164:165], v[114:117], off
	s_nop 0
	s_nop 0
	v_mov_b32_e32 v127, v126
	v_mov_b32_e32 v190, v126
	s_nop 1
	v_permlane16_swap_b32 v127, v190
	v_add_f32_e32 v114, v127, v190
	v_lshlrev_b32_e32 v126, 2, v171
	v_mov_b32_e32 v115, v114
	v_mov_b32_e32 v190, v114
	s_nop 1
	v_permlane32_swap_b32 v190, v115
	v_cvt_pk_bf16_f32 v116, v118, v119
	v_cvt_pk_bf16_f32 v117, v120, v121
	v_cvt_pk_bf16_f32 v118, v138, v139
	v_cvt_pk_bf16_f32 v119, v140, v141
	global_store_dwordx4 v[164:165], v[116:119], off offset:256
	s_and_saveexec_b64 s[20:21], s[0:1]
	s_cbranch_execz .LBB0_942
	v_lshlrev_b64 v[116:117], 7, v[156:157]
	v_lshl_add_u64 v[116:117], s[6:7], 0, v[116:117]
	v_lshl_add_u64 v[116:117], s[18:19], 2, v[116:117]
	s_lshl_b32 s94, s44, 2
	v_lshl_add_u64 v[116:117], v[116:117], 0, s[94:95]
	s_nop 0
	v_add_f32_e32 v114, v114, v115
	global_store_dword v[116:117], v114, off
.LBB0_942:
	s_or_b64 exec, exec, s[20:21]
	v_or_b32_e32 v122, 32, v156
	v_ashrrev_i32_e32 v123, 31, v122
	s_waitcnt lgkmcnt(0)
	v_lshlrev_b64 v[114:115], 11, v[122:123]
	v_lshl_add_u64 v[114:115], s[8:9], 0, v[114:115]
	v_lshl_add_u64 v[124:125], v[158:159], 1, v[114:115]
	global_load_dwordx4 v[118:121], v[124:125], off
	global_load_dwordx4 v[114:117], v[124:125], off offset:256
	v_lshlrev_b32_e32 v128, 16, v134
	v_and_b32_e32 v129, 0xffff0000, v134
	v_lshlrev_b32_e32 v134, 16, v135
	v_and_b32_e32 v135, 0xffff0000, v135
	v_pk_add_f32 v[112:113], v[112:113], v[134:135]
	v_pk_add_f32 v[110:111], v[110:111], v[128:129]
	v_lshlrev_b32_e32 v134, 16, v137
	v_and_b32_e32 v135, 0xffff0000, v137
	v_lshlrev_b32_e32 v128, 16, v136
	v_and_b32_e32 v129, 0xffff0000, v136
	v_pk_add_f32 v[134:135], v[108:109], v[134:135]
	v_mul_f32_e32 v108, v110, v110
	v_mul_f32_e32 v109, v112, v112
	v_pk_add_f32 v[128:129], v[106:107], v[128:129]
	v_fmac_f32_e32 v108, v111, v111
	v_fmac_f32_e32 v109, v113, v113
	v_cvt_pk_bf16_f32 v106, v110, v111
	v_add_f32_e32 v108, v109, v108
	v_mul_f32_e32 v109, v128, v128
	v_mul_f32_e32 v110, v135, v135
	v_fmac_f32_e32 v109, v129, v129
	v_fmac_f32_e32 v110, v134, v134
	v_add_f32_e32 v109, v110, v109
	v_add_f32_e32 v127, v109, v108
	v_lshlrev_b32_e32 v108, 16, v130
	v_and_b32_e32 v109, 0xffff0000, v130
	v_lshlrev_b32_e32 v110, 16, v131
	v_and_b32_e32 v111, 0xffff0000, v131
	v_pk_add_f32 v[104:105], v[104:105], v[110:111]
	v_pk_add_f32 v[102:103], v[102:103], v[108:109]
	v_lshlrev_b32_e32 v108, 16, v132
	v_and_b32_e32 v109, 0xffff0000, v132
	v_cvt_pk_bf16_f32 v107, v112, v113
	v_lshlrev_b32_e32 v110, 16, v133
	v_and_b32_e32 v111, 0xffff0000, v133
	v_pk_add_f32 v[112:113], v[98:99], v[108:109]
	v_mul_f32_e32 v98, v102, v102
	v_mul_f32_e32 v99, v104, v104
	v_pk_add_f32 v[110:111], v[100:101], v[110:111]
	v_fmac_f32_e32 v98, v103, v103
	v_fmac_f32_e32 v99, v105, v105
	v_add_f32_e32 v98, v99, v98
	v_mul_f32_e32 v99, v112, v112
	v_mul_f32_e32 v100, v111, v111
	v_fmac_f32_e32 v99, v113, v113
	v_fmac_f32_e32 v100, v110, v110
	v_add_f32_e32 v99, v100, v99
	v_add_f32_e32 v98, v99, v98
	v_add_f32_e32 v98, v127, v98
	v_cvt_pk_bf16_f32 v108, v128, v129
	v_cvt_pk_bf16_f32 v109, v134, v135
	global_store_dwordx4 v[162:163], v[106:109], off
	v_cvt_pk_bf16_f32 v100, v102, v103
	s_nop 0
	v_mov_b32_e32 v99, v98
	v_mov_b32_e32 v190, v98
	s_nop 1
	v_permlane16_swap_b32 v99, v190
	v_add_f32_e32 v98, v99, v190
	v_mov_b32_e32 v99, v98
	v_mov_b32_e32 v190, v98
	s_nop 1
	v_permlane32_swap_b32 v190, v99
	v_cvt_pk_bf16_f32 v101, v104, v105
	v_cvt_pk_bf16_f32 v102, v112, v113
	v_cvt_pk_bf16_f32 v103, v110, v111
	global_store_dwordx4 v[162:163], v[100:103], off offset:256
	s_and_saveexec_b64 s[20:21], s[0:1]
	s_cbranch_execz .LBB0_944
	v_lshlrev_b64 v[100:101], 7, v[160:161]
	v_lshl_add_u64 v[100:101], s[6:7], 0, v[100:101]
	v_lshl_add_u64 v[100:101], s[18:19], 2, v[100:101]
	s_lshl_b32 s94, s44, 2
	v_lshl_add_u64 v[100:101], v[100:101], 0, s[94:95]
	s_nop 0
	v_add_f32_e32 v98, v98, v99
	global_store_dword v[100:101], v98, off
.LBB0_944:
	s_or_b64 exec, exec, s[20:21]
	v_or_b32_e32 v106, 48, v156
	v_ashrrev_i32_e32 v107, 31, v106
	s_waitcnt lgkmcnt(0)
	v_lshlrev_b64 v[98:99], 11, v[106:107]
	v_lshl_add_u64 v[98:99], s[8:9], 0, v[98:99]
	v_lshl_add_u64 v[108:109], v[158:159], 1, v[98:99]
	global_load_dwordx4 v[102:105], v[108:109], off
	global_load_dwordx4 v[98:101], v[108:109], off offset:256
	s_waitcnt vmcnt(5)
	v_lshlrev_b32_e32 v110, 16, v118
	v_and_b32_e32 v111, 0xffff0000, v118
	v_lshlrev_b32_e32 v112, 16, v119
	v_and_b32_e32 v113, 0xffff0000, v119
	v_pk_add_f32 v[96:97], v[96:97], v[112:113]
	v_pk_add_f32 v[94:95], v[94:95], v[110:111]
	v_lshlrev_b32_e32 v112, 16, v121
	v_and_b32_e32 v113, 0xffff0000, v121
	v_lshlrev_b32_e32 v110, 16, v120
	v_and_b32_e32 v111, 0xffff0000, v120
	v_pk_add_f32 v[112:113], v[92:93], v[112:113]
	v_mul_f32_e32 v92, v94, v94
	v_mul_f32_e32 v93, v96, v96
	v_pk_add_f32 v[110:111], v[90:91], v[110:111]
	v_fmac_f32_e32 v92, v95, v95
	v_fmac_f32_e32 v93, v97, v97
	v_cvt_pk_bf16_f32 v90, v94, v95
	v_add_f32_e32 v92, v93, v92
	v_mul_f32_e32 v93, v110, v110
	v_mul_f32_e32 v94, v113, v113
	v_fmac_f32_e32 v93, v111, v111
	v_fmac_f32_e32 v94, v112, v112
	v_add_f32_e32 v93, v94, v93
	v_add_f32_e32 v118, v93, v92
	s_waitcnt vmcnt(4)
	v_lshlrev_b32_e32 v92, 16, v114
	v_and_b32_e32 v93, 0xffff0000, v114
	v_lshlrev_b32_e32 v94, 16, v115
	v_and_b32_e32 v95, 0xffff0000, v115
	v_pk_add_f32 v[88:89], v[88:89], v[94:95]
	v_pk_add_f32 v[86:87], v[86:87], v[92:93]
	v_lshlrev_b32_e32 v92, 16, v116
	v_and_b32_e32 v93, 0xffff0000, v116
	v_cvt_pk_bf16_f32 v91, v96, v97
	v_lshlrev_b32_e32 v94, 16, v117
	v_and_b32_e32 v95, 0xffff0000, v117
	v_pk_add_f32 v[96:97], v[82:83], v[92:93]
	v_mul_f32_e32 v82, v86, v86
	v_mul_f32_e32 v83, v88, v88
	v_pk_add_f32 v[94:95], v[84:85], v[94:95]
	v_fmac_f32_e32 v82, v87, v87
	v_fmac_f32_e32 v83, v89, v89
	v_add_f32_e32 v82, v83, v82
	v_mul_f32_e32 v83, v96, v96
	v_mul_f32_e32 v84, v95, v95
	v_fmac_f32_e32 v83, v97, v97
	v_fmac_f32_e32 v84, v94, v94
	v_add_f32_e32 v83, v84, v83
	v_add_f32_e32 v82, v83, v82
	v_add_f32_e32 v82, v118, v82
	v_cvt_pk_bf16_f32 v92, v110, v111
	v_cvt_pk_bf16_f32 v93, v112, v113
	global_store_dwordx4 v[124:125], v[90:93], off
	v_cvt_pk_bf16_f32 v84, v86, v87
	s_nop 0
	v_mov_b32_e32 v83, v82
	v_mov_b32_e32 v190, v82
	s_nop 1
	v_permlane16_swap_b32 v83, v190
	v_add_f32_e32 v82, v83, v190
	v_mov_b32_e32 v83, v82
	v_mov_b32_e32 v190, v82
	s_nop 1
	v_permlane32_swap_b32 v190, v83
	v_cvt_pk_bf16_f32 v85, v88, v89
	v_cvt_pk_bf16_f32 v86, v96, v97
	v_cvt_pk_bf16_f32 v87, v94, v95
	global_store_dwordx4 v[124:125], v[84:87], off offset:256
	s_and_saveexec_b64 s[20:21], s[0:1]
	s_cbranch_execz .LBB0_946
	v_lshlrev_b64 v[84:85], 7, v[122:123]
	v_lshl_add_u64 v[84:85], s[6:7], 0, v[84:85]
	v_lshl_add_u64 v[84:85], s[18:19], 2, v[84:85]
	s_lshl_b32 s94, s44, 2
	v_lshl_add_u64 v[84:85], v[84:85], 0, s[94:95]
	s_nop 0
	v_add_f32_e32 v82, v82, v83
	global_store_dword v[84:85], v82, off
.LBB0_946:
	s_or_b64 exec, exec, s[20:21]
	v_add_u32_e32 v90, 0x80, v156
	v_ashrrev_i32_e32 v91, 31, v90
	s_waitcnt lgkmcnt(0)
	v_lshlrev_b64 v[82:83], 11, v[90:91]
	v_lshl_add_u64 v[82:83], s[8:9], 0, v[82:83]
	v_lshl_add_u64 v[92:93], v[158:159], 1, v[82:83]
	global_load_dwordx4 v[86:89], v[92:93], off
	global_load_dwordx4 v[82:85], v[92:93], off offset:256
	s_waitcnt vmcnt(5)
	v_lshlrev_b32_e32 v94, 16, v102
	v_and_b32_e32 v95, 0xffff0000, v102
	v_lshlrev_b32_e32 v96, 16, v103
	v_and_b32_e32 v97, 0xffff0000, v103
	v_pk_add_f32 v[80:81], v[80:81], v[96:97]
	v_pk_add_f32 v[78:79], v[78:79], v[94:95]
	v_lshlrev_b32_e32 v96, 16, v105
	v_and_b32_e32 v97, 0xffff0000, v105
	v_lshlrev_b32_e32 v94, 16, v104
	v_and_b32_e32 v95, 0xffff0000, v104
	v_pk_add_f32 v[96:97], v[76:77], v[96:97]
	v_mul_f32_e32 v76, v78, v78
	v_mul_f32_e32 v77, v80, v80
	v_pk_add_f32 v[94:95], v[74:75], v[94:95]
	v_fmac_f32_e32 v76, v79, v79
	v_fmac_f32_e32 v77, v81, v81
	v_cvt_pk_bf16_f32 v74, v78, v79
	v_add_f32_e32 v76, v77, v76
	v_mul_f32_e32 v77, v94, v94
	v_mul_f32_e32 v78, v97, v97
	v_fmac_f32_e32 v77, v95, v95
	v_fmac_f32_e32 v78, v96, v96
	v_add_f32_e32 v77, v78, v77
	v_add_f32_e32 v102, v77, v76
	s_waitcnt vmcnt(4)
	v_lshlrev_b32_e32 v76, 16, v98
	v_and_b32_e32 v77, 0xffff0000, v98
	v_lshlrev_b32_e32 v78, 16, v99
	v_and_b32_e32 v79, 0xffff0000, v99
	v_pk_add_f32 v[72:73], v[72:73], v[78:79]
	v_pk_add_f32 v[70:71], v[70:71], v[76:77]
	v_lshlrev_b32_e32 v76, 16, v100
	v_and_b32_e32 v77, 0xffff0000, v100
	v_cvt_pk_bf16_f32 v75, v80, v81
	v_lshlrev_b32_e32 v78, 16, v101
	v_and_b32_e32 v79, 0xffff0000, v101
	v_pk_add_f32 v[80:81], v[66:67], v[76:77]
	v_mul_f32_e32 v66, v70, v70
	v_mul_f32_e32 v67, v72, v72
	v_pk_add_f32 v[78:79], v[68:69], v[78:79]
	v_fmac_f32_e32 v66, v71, v71
	v_fmac_f32_e32 v67, v73, v73
	v_add_f32_e32 v66, v67, v66
	v_mul_f32_e32 v67, v80, v80
	v_mul_f32_e32 v68, v79, v79
	v_fmac_f32_e32 v67, v81, v81
	v_fmac_f32_e32 v68, v78, v78
	v_add_f32_e32 v67, v68, v67
	v_add_f32_e32 v66, v67, v66
	v_add_f32_e32 v66, v102, v66
	v_cvt_pk_bf16_f32 v76, v94, v95
	v_cvt_pk_bf16_f32 v77, v96, v97
	global_store_dwordx4 v[108:109], v[74:77], off
	v_cvt_pk_bf16_f32 v68, v70, v71
	s_nop 0
	v_mov_b32_e32 v67, v66
	v_mov_b32_e32 v190, v66
	s_nop 1
	v_permlane16_swap_b32 v67, v190
	v_add_f32_e32 v66, v67, v190
	v_mov_b32_e32 v67, v66
	v_mov_b32_e32 v190, v66
	s_nop 1
	v_permlane32_swap_b32 v190, v67
	v_cvt_pk_bf16_f32 v69, v72, v73
	v_cvt_pk_bf16_f32 v70, v80, v81
	v_cvt_pk_bf16_f32 v71, v78, v79
	global_store_dwordx4 v[108:109], v[68:71], off offset:256
	s_and_saveexec_b64 s[20:21], s[0:1]
	s_cbranch_execz .LBB0_948
	v_lshlrev_b64 v[68:69], 7, v[106:107]
	v_lshl_add_u64 v[68:69], s[6:7], 0, v[68:69]
	v_lshl_add_u64 v[68:69], s[18:19], 2, v[68:69]
	s_lshl_b32 s94, s44, 2
	v_lshl_add_u64 v[68:69], v[68:69], 0, s[94:95]
	s_nop 0
	v_add_f32_e32 v66, v66, v67
	global_store_dword v[68:69], v66, off
.LBB0_948:
	s_or_b64 exec, exec, s[20:21]
	v_or_b32_e32 v66, 16, v90
	s_waitcnt lgkmcnt(0)
	v_ashrrev_i32_e32 v67, 31, v66
	v_lshlrev_b64 v[66:67], 11, v[66:67]
	v_lshl_add_u64 v[66:67], s[8:9], 0, v[66:67]
	v_lshl_add_u64 v[74:75], v[158:159], 1, v[66:67]
	global_load_dwordx4 v[70:73], v[74:75], off
	global_load_dwordx4 v[66:69], v[74:75], off offset:256
	s_waitcnt vmcnt(5)
	v_lshlrev_b32_e32 v76, 16, v86
	v_and_b32_e32 v77, 0xffff0000, v86
	v_lshlrev_b32_e32 v78, 16, v87
	v_and_b32_e32 v79, 0xffff0000, v87
	v_pk_add_f32 v[64:65], v[64:65], v[78:79]
	v_pk_add_f32 v[62:63], v[62:63], v[76:77]
	v_lshlrev_b32_e32 v78, 16, v89
	v_and_b32_e32 v79, 0xffff0000, v89
	v_lshlrev_b32_e32 v76, 16, v88
	v_and_b32_e32 v77, 0xffff0000, v88
	v_pk_add_f32 v[78:79], v[60:61], v[78:79]
	v_mul_f32_e32 v60, v62, v62
	v_mul_f32_e32 v61, v64, v64
	v_pk_add_f32 v[76:77], v[58:59], v[76:77]
	v_fmac_f32_e32 v60, v63, v63
	v_fmac_f32_e32 v61, v65, v65
	v_cvt_pk_bf16_f32 v58, v62, v63
	v_add_f32_e32 v60, v61, v60
	v_mul_f32_e32 v61, v76, v76
	v_mul_f32_e32 v62, v79, v79
	v_fmac_f32_e32 v61, v77, v77
	v_fmac_f32_e32 v62, v78, v78
	v_add_f32_e32 v61, v62, v61
	v_add_f32_e32 v80, v61, v60
	s_waitcnt vmcnt(4)
	v_lshlrev_b32_e32 v60, 16, v82
	v_and_b32_e32 v61, 0xffff0000, v82
	v_lshlrev_b32_e32 v62, 16, v83
	v_and_b32_e32 v63, 0xffff0000, v83
	v_pk_add_f32 v[56:57], v[56:57], v[62:63]
	v_pk_add_f32 v[54:55], v[54:55], v[60:61]
	v_lshlrev_b32_e32 v60, 16, v84
	v_and_b32_e32 v61, 0xffff0000, v84
	v_cvt_pk_bf16_f32 v59, v64, v65
	v_lshlrev_b32_e32 v62, 16, v85
	v_and_b32_e32 v63, 0xffff0000, v85
	v_pk_add_f32 v[64:65], v[50:51], v[60:61]
	v_mul_f32_e32 v50, v54, v54
	v_mul_f32_e32 v51, v56, v56
	v_pk_add_f32 v[62:63], v[52:53], v[62:63]
	v_fmac_f32_e32 v50, v55, v55
	v_fmac_f32_e32 v51, v57, v57
	v_add_f32_e32 v50, v51, v50
	v_mul_f32_e32 v51, v64, v64
	v_mul_f32_e32 v52, v63, v63
	v_fmac_f32_e32 v51, v65, v65
	v_fmac_f32_e32 v52, v62, v62
	v_add_f32_e32 v51, v52, v51
	v_add_f32_e32 v50, v51, v50
	v_add_f32_e32 v50, v80, v50
	v_cvt_pk_bf16_f32 v60, v76, v77
	v_cvt_pk_bf16_f32 v61, v78, v79
	global_store_dwordx4 v[92:93], v[58:61], off
	v_cvt_pk_bf16_f32 v52, v54, v55
	s_nop 0
	v_mov_b32_e32 v51, v50
	v_mov_b32_e32 v190, v50
	s_nop 1
	v_permlane16_swap_b32 v51, v190
	v_add_f32_e32 v50, v51, v190
	v_mov_b32_e32 v51, v50
	v_mov_b32_e32 v190, v50
	s_nop 1
	v_permlane32_swap_b32 v190, v51
	v_cvt_pk_bf16_f32 v53, v56, v57
	v_cvt_pk_bf16_f32 v54, v64, v65
	v_cvt_pk_bf16_f32 v55, v62, v63
	global_store_dwordx4 v[92:93], v[52:55], off offset:256
	s_and_saveexec_b64 s[20:21], s[0:1]
	s_cbranch_execz .LBB0_950
	v_lshlrev_b64 v[52:53], 7, v[90:91]
	v_lshl_add_u64 v[52:53], s[6:7], 0, v[52:53]
	v_lshl_add_u64 v[52:53], s[18:19], 2, v[52:53]
	s_lshl_b32 s94, s44, 2
	v_lshl_add_u64 v[52:53], v[52:53], 0, s[94:95]
	s_nop 0
	v_add_f32_e32 v50, v50, v51
	global_store_dword v[52:53], v50, off
.LBB0_950:
	s_or_b64 exec, exec, s[20:21]
	v_or_b32_e32 v50, 32, v90
	s_waitcnt lgkmcnt(0)
	v_ashrrev_i32_e32 v51, 31, v50
	v_lshlrev_b64 v[50:51], 11, v[50:51]
	v_lshl_add_u64 v[50:51], s[8:9], 0, v[50:51]
	v_lshl_add_u64 v[58:59], v[158:159], 1, v[50:51]
	global_load_dwordx4 v[54:57], v[58:59], off
	global_load_dwordx4 v[50:53], v[58:59], off offset:256
	s_waitcnt vmcnt(5)
	v_lshlrev_b32_e32 v60, 16, v70
	v_and_b32_e32 v61, 0xffff0000, v70
	v_lshlrev_b32_e32 v62, 16, v71
	v_and_b32_e32 v63, 0xffff0000, v71
	v_pk_add_f32 v[48:49], v[48:49], v[62:63]
	v_pk_add_f32 v[46:47], v[46:47], v[60:61]
	v_lshlrev_b32_e32 v62, 16, v73
	v_and_b32_e32 v63, 0xffff0000, v73
	v_lshlrev_b32_e32 v60, 16, v72
	v_and_b32_e32 v61, 0xffff0000, v72
	v_pk_add_f32 v[62:63], v[44:45], v[62:63]
	v_mul_f32_e32 v44, v46, v46
	v_mul_f32_e32 v45, v48, v48
	v_pk_add_f32 v[60:61], v[42:43], v[60:61]
	v_fmac_f32_e32 v44, v47, v47
	v_fmac_f32_e32 v45, v49, v49
	v_cvt_pk_bf16_f32 v42, v46, v47
	v_add_f32_e32 v44, v45, v44
	v_mul_f32_e32 v45, v60, v60
	v_mul_f32_e32 v46, v63, v63
	v_fmac_f32_e32 v45, v61, v61
	v_fmac_f32_e32 v46, v62, v62
	v_add_f32_e32 v45, v46, v45
	v_add_f32_e32 v64, v45, v44
	s_waitcnt vmcnt(4)
	v_lshlrev_b32_e32 v44, 16, v66
	v_and_b32_e32 v45, 0xffff0000, v66
	v_lshlrev_b32_e32 v46, 16, v67
	v_and_b32_e32 v47, 0xffff0000, v67
	v_pk_add_f32 v[40:41], v[40:41], v[46:47]
	v_pk_add_f32 v[38:39], v[38:39], v[44:45]
	v_lshlrev_b32_e32 v44, 16, v68
	v_and_b32_e32 v45, 0xffff0000, v68
	v_cvt_pk_bf16_f32 v43, v48, v49
	v_lshlrev_b32_e32 v46, 16, v69
	v_and_b32_e32 v47, 0xffff0000, v69
	v_pk_add_f32 v[48:49], v[34:35], v[44:45]
	v_mul_f32_e32 v34, v38, v38
	v_mul_f32_e32 v35, v40, v40
	v_pk_add_f32 v[46:47], v[36:37], v[46:47]
	v_fmac_f32_e32 v34, v39, v39
	v_fmac_f32_e32 v35, v41, v41
	v_add_f32_e32 v34, v35, v34
	v_mul_f32_e32 v35, v48, v48
	v_mul_f32_e32 v36, v47, v47
	v_fmac_f32_e32 v35, v49, v49
	v_fmac_f32_e32 v36, v46, v46
	v_add_f32_e32 v35, v36, v35
	v_add_f32_e32 v34, v35, v34
	v_add_f32_e32 v34, v64, v34
	v_cvt_pk_bf16_f32 v44, v60, v61
	v_cvt_pk_bf16_f32 v45, v62, v63
	global_store_dwordx4 v[74:75], v[42:45], off
	v_cvt_pk_bf16_f32 v36, v38, v39
	s_nop 0
	v_mov_b32_e32 v35, v34
	v_mov_b32_e32 v190, v34
	s_nop 1
	v_permlane16_swap_b32 v35, v190
	v_add_f32_e32 v34, v35, v190
	v_mov_b32_e32 v35, v34
	v_mov_b32_e32 v190, v34
	s_nop 1
	v_permlane32_swap_b32 v190, v35
	v_cvt_pk_bf16_f32 v37, v40, v41
	v_cvt_pk_bf16_f32 v38, v48, v49
	v_cvt_pk_bf16_f32 v39, v46, v47
	global_store_dwordx4 v[74:75], v[36:39], off offset:256
	s_and_saveexec_b64 s[20:21], s[0:1]
	s_cbranch_execz .LBB0_952
	v_add_u32_e32 v36, 0x90, v156
	v_ashrrev_i32_e32 v37, 31, v36
	v_lshlrev_b64 v[36:37], 7, v[36:37]
	v_lshl_add_u64 v[36:37], s[6:7], 0, v[36:37]
	v_lshl_add_u64 v[36:37], s[18:19], 2, v[36:37]
	s_lshl_b32 s94, s44, 2
	v_lshl_add_u64 v[36:37], v[36:37], 0, s[94:95]
	s_nop 0
	v_add_f32_e32 v34, v34, v35
	global_store_dword v[36:37], v34, off
.LBB0_952:
	s_or_b64 exec, exec, s[20:21]
	v_or_b32_e32 v34, 48, v90
	s_waitcnt lgkmcnt(0)
	v_ashrrev_i32_e32 v35, 31, v34
	v_lshlrev_b64 v[34:35], 11, v[34:35]
	v_lshl_add_u64 v[34:35], s[8:9], 0, v[34:35]
	v_lshl_add_u64 v[42:43], v[158:159], 1, v[34:35]
	global_load_dwordx4 v[38:41], v[42:43], off
	global_load_dwordx4 v[34:37], v[42:43], off offset:256
	s_waitcnt vmcnt(5)
	v_lshlrev_b32_e32 v44, 16, v54
	v_and_b32_e32 v45, 0xffff0000, v54
	v_lshlrev_b32_e32 v46, 16, v55
	v_and_b32_e32 v47, 0xffff0000, v55
	v_pk_add_f32 v[32:33], v[32:33], v[46:47]
	v_pk_add_f32 v[30:31], v[30:31], v[44:45]
	v_lshlrev_b32_e32 v46, 16, v57
	v_and_b32_e32 v47, 0xffff0000, v57
	v_lshlrev_b32_e32 v44, 16, v56
	v_and_b32_e32 v45, 0xffff0000, v56
	v_pk_add_f32 v[46:47], v[28:29], v[46:47]
	v_mul_f32_e32 v28, v30, v30
	v_mul_f32_e32 v29, v32, v32
	v_pk_add_f32 v[44:45], v[26:27], v[44:45]
	v_fmac_f32_e32 v28, v31, v31
	v_fmac_f32_e32 v29, v33, v33
	v_cvt_pk_bf16_f32 v26, v30, v31
	v_add_f32_e32 v28, v29, v28
	v_mul_f32_e32 v29, v44, v44
	v_mul_f32_e32 v30, v47, v47
	v_fmac_f32_e32 v29, v45, v45
	v_fmac_f32_e32 v30, v46, v46
	v_add_f32_e32 v29, v30, v29
	v_add_f32_e32 v48, v29, v28
	s_waitcnt vmcnt(4)
	v_lshlrev_b32_e32 v28, 16, v50
	v_and_b32_e32 v29, 0xffff0000, v50
	v_lshlrev_b32_e32 v30, 16, v51
	v_and_b32_e32 v31, 0xffff0000, v51
	v_pk_add_f32 v[24:25], v[24:25], v[30:31]
	v_pk_add_f32 v[22:23], v[22:23], v[28:29]
	v_lshlrev_b32_e32 v28, 16, v52
	v_and_b32_e32 v29, 0xffff0000, v52
	v_cvt_pk_bf16_f32 v27, v32, v33
	v_lshlrev_b32_e32 v30, 16, v53
	v_and_b32_e32 v31, 0xffff0000, v53
	v_pk_add_f32 v[32:33], v[18:19], v[28:29]
	v_mul_f32_e32 v18, v22, v22
	v_mul_f32_e32 v19, v24, v24
	v_pk_add_f32 v[30:31], v[20:21], v[30:31]
	v_fmac_f32_e32 v18, v23, v23
	v_fmac_f32_e32 v19, v25, v25
	v_add_f32_e32 v18, v19, v18
	v_mul_f32_e32 v19, v32, v32
	v_mul_f32_e32 v20, v31, v31
	v_fmac_f32_e32 v19, v33, v33
	v_fmac_f32_e32 v20, v30, v30
	v_add_f32_e32 v19, v20, v19
	v_add_f32_e32 v18, v19, v18
	v_add_f32_e32 v18, v48, v18
	v_cvt_pk_bf16_f32 v28, v44, v45
	v_cvt_pk_bf16_f32 v29, v46, v47
	global_store_dwordx4 v[58:59], v[26:29], off
	v_cvt_pk_bf16_f32 v20, v22, v23
	s_nop 0
	v_mov_b32_e32 v19, v18
	v_mov_b32_e32 v190, v18
	s_nop 1
	v_permlane16_swap_b32 v19, v190
	v_add_f32_e32 v18, v19, v190
	v_mov_b32_e32 v19, v18
	v_mov_b32_e32 v190, v18
	s_nop 1
	v_permlane32_swap_b32 v190, v19
	v_cvt_pk_bf16_f32 v21, v24, v25
	v_cvt_pk_bf16_f32 v22, v32, v33
	v_cvt_pk_bf16_f32 v23, v30, v31
	global_store_dwordx4 v[58:59], v[20:23], off offset:256
	s_and_saveexec_b64 s[20:21], s[0:1]
	s_cbranch_execz .LBB0_954
	v_add_u32_e32 v20, 0xa0, v156
	v_ashrrev_i32_e32 v21, 31, v20
	v_lshlrev_b64 v[20:21], 7, v[20:21]
	v_lshl_add_u64 v[20:21], s[6:7], 0, v[20:21]
	v_lshl_add_u64 v[20:21], s[18:19], 2, v[20:21]
	s_lshl_b32 s94, s44, 2
	v_lshl_add_u64 v[20:21], v[20:21], 0, s[94:95]
	s_nop 0
	v_add_f32_e32 v18, v18, v19
	global_store_dword v[20:21], v18, off
.LBB0_954:
	s_or_b64 exec, exec, s[20:21]
	s_waitcnt vmcnt(3)
	v_lshlrev_b32_e32 v18, 16, v38
	s_waitcnt lgkmcnt(0)
	v_and_b32_e32 v19, 0xffff0000, v38
	v_lshlrev_b32_e32 v20, 16, v39
	v_and_b32_e32 v21, 0xffff0000, v39
	v_pk_add_f32 v[16:17], v[16:17], v[20:21]
	v_pk_add_f32 v[14:15], v[14:15], v[18:19]
	v_lshlrev_b32_e32 v20, 16, v41
	v_and_b32_e32 v21, 0xffff0000, v41
	v_lshlrev_b32_e32 v18, 16, v40
	v_and_b32_e32 v19, 0xffff0000, v40
	v_pk_add_f32 v[20:21], v[12:13], v[20:21]
	v_mul_f32_e32 v12, v14, v14
	v_mul_f32_e32 v13, v16, v16
	v_pk_add_f32 v[18:19], v[10:11], v[18:19]
	v_fmac_f32_e32 v12, v15, v15
	v_fmac_f32_e32 v13, v17, v17
	v_cvt_pk_bf16_f32 v10, v14, v15
	v_add_f32_e32 v12, v13, v12
	v_mul_f32_e32 v13, v18, v18
	v_mul_f32_e32 v14, v21, v21
	v_fmac_f32_e32 v13, v19, v19
	v_fmac_f32_e32 v14, v20, v20
	v_add_f32_e32 v13, v14, v13
	v_add_f32_e32 v22, v13, v12
	s_waitcnt vmcnt(2)
	v_lshlrev_b32_e32 v12, 16, v34
	v_and_b32_e32 v13, 0xffff0000, v34
	v_lshlrev_b32_e32 v14, 16, v35
	v_and_b32_e32 v15, 0xffff0000, v35
	v_pk_add_f32 v[8:9], v[8:9], v[14:15]
	v_pk_add_f32 v[6:7], v[6:7], v[12:13]
	v_lshlrev_b32_e32 v12, 16, v36
	v_and_b32_e32 v13, 0xffff0000, v36
	v_cvt_pk_bf16_f32 v11, v16, v17
	v_lshlrev_b32_e32 v14, 16, v37
	v_and_b32_e32 v15, 0xffff0000, v37
	v_pk_add_f32 v[16:17], v[2:3], v[12:13]
	v_mul_f32_e32 v2, v6, v6
	v_mul_f32_e32 v3, v8, v8
	v_pk_add_f32 v[14:15], v[4:5], v[14:15]
	v_fmac_f32_e32 v2, v7, v7
	v_fmac_f32_e32 v3, v9, v9
	v_add_f32_e32 v2, v3, v2
	v_mul_f32_e32 v3, v16, v16
	v_mul_f32_e32 v4, v15, v15
	v_fmac_f32_e32 v3, v17, v17
	v_fmac_f32_e32 v4, v14, v14
	v_add_f32_e32 v3, v4, v3
	v_add_f32_e32 v2, v3, v2
	v_add_f32_e32 v2, v22, v2
	v_cvt_pk_bf16_f32 v12, v18, v19
	v_cvt_pk_bf16_f32 v13, v20, v21
	global_store_dwordx4 v[42:43], v[10:13], off
	v_cvt_pk_bf16_f32 v4, v6, v7
	s_nop 0
	v_mov_b32_e32 v3, v2
	v_mov_b32_e32 v190, v2
	s_nop 1
	v_permlane16_swap_b32 v3, v190
	v_add_f32_e32 v2, v3, v190
	v_mov_b32_e32 v3, v2
	v_mov_b32_e32 v190, v2
	s_nop 1
	v_permlane32_swap_b32 v190, v3
	v_cvt_pk_bf16_f32 v5, v8, v9
	v_cvt_pk_bf16_f32 v6, v16, v17
	v_cvt_pk_bf16_f32 v7, v14, v15
	global_store_dwordx4 v[42:43], v[4:7], off offset:256
	s_and_saveexec_b64 s[20:21], s[0:1]
	s_cbranch_execz .LBB0_931
	v_add_u32_e32 v4, 0xb0, v156
	v_ashrrev_i32_e32 v5, 31, v4
	v_lshlrev_b64 v[4:5], 7, v[4:5]
	v_lshl_add_u64 v[4:5], s[6:7], 0, v[4:5]
	v_lshl_add_u64 v[4:5], s[18:19], 2, v[4:5]
	s_lshl_b32 s94, s44, 2
	v_lshl_add_u64 v[4:5], v[4:5], 0, s[94:95]
	s_nop 0
	v_add_f32_e32 v2, v2, v3
	global_store_dword v[4:5], v2, off
	s_branch .LBB0_931
